# GDN token tail reordered: dependent ops >= 2 issue slots apart, y-output path interleaved with the state update
# baseline (speedup 1.0000x reference)
.Lgd2_loop:
	global_load_dword v108, v36, s[8:9]
	global_load_dword v109, v36, s[8:9] offset:-2048
	global_load_dword v111, v104, s[8:9] offset:2048
	global_load_dword v110, v37, s[10:11]
	global_load_dword v112, v105, s[10:11]
	global_load_dword v113, v106, s[12:13]
	s_add_u32 s8, s8, 0xc000
	s_addc_u32 s9, s9, 0
	s_add_u32 s10, s10, 0x20000
	s_addc_u32 s11, s11, 0
	s_add_u32 s12, s12, 0x400
	s_addc_u32 s13, s13, 0
	s_waitcnt lgkmcnt(5)
	v_pk_mul_f32 v[38:39], v[6:7], v[56:57] op_sel_hi:[1,0]
	v_pk_mul_f32 v[40:41], v[6:7], v[56:57] op_sel:[0,1] op_sel_hi:[1,1]
	v_pk_fma_f32 v[38:39], v[8:9], v[58:59], v[38:39] op_sel_hi:[1,0,1]
	v_pk_fma_f32 v[40:41], v[8:9], v[58:59], v[40:41] op_sel:[0,1,0] op_sel_hi:[1,1,1]
	s_waitcnt lgkmcnt(4)
	v_pk_fma_f32 v[38:39], v[10:11], v[60:61], v[38:39] op_sel_hi:[1,0,1]
	v_pk_fma_f32 v[40:41], v[10:11], v[60:61], v[40:41] op_sel:[0,1,0] op_sel_hi:[1,1,1]
	v_pk_fma_f32 v[38:39], v[12:13], v[62:63], v[38:39] op_sel_hi:[1,0,1]
	v_pk_fma_f32 v[40:41], v[12:13], v[62:63], v[40:41] op_sel:[0,1,0] op_sel_hi:[1,1,1]
	s_waitcnt lgkmcnt(3)
	v_pk_fma_f32 v[38:39], v[14:15], v[64:65], v[38:39] op_sel_hi:[1,0,1]
	v_pk_fma_f32 v[40:41], v[14:15], v[64:65], v[40:41] op_sel:[0,1,0] op_sel_hi:[1,1,1]
	v_pk_fma_f32 v[38:39], v[16:17], v[66:67], v[38:39] op_sel_hi:[1,0,1]
	v_pk_fma_f32 v[40:41], v[16:17], v[66:67], v[40:41] op_sel:[0,1,0] op_sel_hi:[1,1,1]
	s_waitcnt lgkmcnt(2)
	v_pk_fma_f32 v[38:39], v[18:19], v[68:69], v[38:39] op_sel_hi:[1,0,1]
	v_pk_fma_f32 v[40:41], v[18:19], v[68:69], v[40:41] op_sel:[0,1,0] op_sel_hi:[1,1,1]
	v_pk_fma_f32 v[38:39], v[20:21], v[70:71], v[38:39] op_sel_hi:[1,0,1]
	v_pk_fma_f32 v[40:41], v[20:21], v[70:71], v[40:41] op_sel:[0,1,0] op_sel_hi:[1,1,1]
	s_waitcnt lgkmcnt(0)
	v_mul_f32_e32 v50, v76, v51
	v_add_f32_dpp v38, v38, v38 row_ror:8 row_mask:0xf bank_mask:0x3 bound_ctrl:1
	v_add_f32_dpp v39, v39, v39 row_ror:8 row_mask:0xf bank_mask:0x3 bound_ctrl:1
	v_add_f32_dpp v38, v40, v40 row_ror:8 row_mask:0xf bank_mask:0xc bound_ctrl:1
	v_add_f32_dpp v39, v41, v41 row_ror:8 row_mask:0xf bank_mask:0xc bound_ctrl:1
	ds_read_b128 v[80:83], v2 offset:1280
	v_add_f32_dpp v38, v38, v38 row_half_mirror row_mask:0xf bank_mask:0x5 bound_ctrl:1
	v_add_f32_dpp v38, v39, v39 row_half_mirror row_mask:0xf bank_mask:0xa bound_ctrl:1
	ds_read_b128 v[84:87], v2 offset:1536
	ds_read_b128 v[88:91], v2 offset:1792
	v_add_f32_dpp v38, v38, v38 quad_perm:[1,0,3,2] row_mask:0xf bank_mask:0xf bound_ctrl:1
	ds_read_b128 v[92:95], v2 offset:2048
	ds_read_b64 v[96:97], v3 offset:12800
	v_add_f32_dpp v38, v38, v38 quad_perm:[2,3,0,1] row_mask:0xf bank_mask:0xf bound_ctrl:1
	ds_read_b128 v[100:103], v1 offset:14608
	v_cmp_gt_f32_e32 vcc, 0x2b8cbccc, v50
	v_fmac_f32_dpp v72, -v38, v50 row_newbcast:0 row_mask:0xf bank_mask:0xf bound_ctrl:1
	v_fmac_f32_dpp v73, -v38, v50 row_newbcast:4 row_mask:0xf bank_mask:0xf bound_ctrl:1
	v_rcp_f32_e32 v52, v50
	s_add_u32 s14, s14, 0x1000
	v_pk_mul_f32 v[44:45], v[72:73], v[76:77] op_sel:[0,1] op_sel_hi:[1,1]
	s_addc_u32 s15, s15, 0
	s_cbranch_vccnz .Lgd2_rare0_0
.Lgd2_back0_0:
	v_pk_mul_f32 v[46:47], v[44:45], v[52:53] op_sel_hi:[1,0]
	v_pk_mul_f32 v[48:49], v[44:45], v[78:79] op_sel_hi:[1,0]
	v_pk_fma_f32 v[6:7], v[56:57], v[46:47], v[6:7] op_sel_hi:[0,1,1]
	v_pk_fma_f32 v[8:9], v[58:59], v[46:47], v[8:9] op_sel_hi:[0,1,1]
	v_fmac_f32_dpp v48, v38, v50 row_newbcast:8 row_mask:0xf bank_mask:0xf bound_ctrl:1
	v_pk_fma_f32 v[10:11], v[60:61], v[46:47], v[10:11] op_sel_hi:[0,1,1]
	v_fmac_f32_dpp v49, v38, v50 row_newbcast:12 row_mask:0xf bank_mask:0xf bound_ctrl:1
	v_pk_fma_f32 v[12:13], v[62:63], v[46:47], v[12:13] op_sel_hi:[0,1,1]
	v_pk_fma_f32 v[14:15], v[64:65], v[46:47], v[14:15] op_sel_hi:[0,1,1]
	v_cvt_pk_bf16_f32 v54, v48, v49
	v_pk_fma_f32 v[16:17], v[66:67], v[46:47], v[16:17] op_sel_hi:[0,1,1]
	v_pk_fma_f32 v[18:19], v[68:69], v[46:47], v[18:19] op_sel_hi:[0,1,1]
	v_pk_fma_f32 v[20:21], v[70:71], v[46:47], v[20:21] op_sel_hi:[0,1,1]
	global_store_dword v154, v54, s[14:15] offset:-4096
	s_waitcnt lgkmcnt(5)
	v_pk_mul_f32 v[38:39], v[6:7], v[80:81] op_sel_hi:[1,0]
	v_pk_mul_f32 v[40:41], v[6:7], v[80:81] op_sel:[0,1] op_sel_hi:[1,1]
	v_pk_fma_f32 v[38:39], v[8:9], v[82:83], v[38:39] op_sel_hi:[1,0,1]
	v_pk_fma_f32 v[40:41], v[8:9], v[82:83], v[40:41] op_sel:[0,1,0] op_sel_hi:[1,1,1]
	s_waitcnt lgkmcnt(4)
	v_pk_fma_f32 v[38:39], v[10:11], v[84:85], v[38:39] op_sel_hi:[1,0,1]
	v_pk_fma_f32 v[40:41], v[10:11], v[84:85], v[40:41] op_sel:[0,1,0] op_sel_hi:[1,1,1]
	v_pk_fma_f32 v[38:39], v[12:13], v[86:87], v[38:39] op_sel_hi:[1,0,1]
	v_pk_fma_f32 v[40:41], v[12:13], v[86:87], v[40:41] op_sel:[0,1,0] op_sel_hi:[1,1,1]
	s_waitcnt lgkmcnt(3)
	v_pk_fma_f32 v[38:39], v[14:15], v[88:89], v[38:39] op_sel_hi:[1,0,1]
	v_pk_fma_f32 v[40:41], v[14:15], v[88:89], v[40:41] op_sel:[0,1,0] op_sel_hi:[1,1,1]
	v_pk_fma_f32 v[38:39], v[16:17], v[90:91], v[38:39] op_sel_hi:[1,0,1]
	v_pk_fma_f32 v[40:41], v[16:17], v[90:91], v[40:41] op_sel:[0,1,0] op_sel_hi:[1,1,1]
	s_waitcnt lgkmcnt(2)
	v_pk_fma_f32 v[38:39], v[18:19], v[92:93], v[38:39] op_sel_hi:[1,0,1]
	v_pk_fma_f32 v[40:41], v[18:19], v[92:93], v[40:41] op_sel:[0,1,0] op_sel_hi:[1,1,1]
	v_pk_fma_f32 v[38:39], v[20:21], v[94:95], v[38:39] op_sel_hi:[1,0,1]
	v_pk_fma_f32 v[40:41], v[20:21], v[94:95], v[40:41] op_sel:[0,1,0] op_sel_hi:[1,1,1]
	s_waitcnt lgkmcnt(0)
	v_mul_f32_e32 v51, v100, v50
	v_add_f32_dpp v38, v38, v38 row_ror:8 row_mask:0xf bank_mask:0x3 bound_ctrl:1
	v_add_f32_dpp v39, v39, v39 row_ror:8 row_mask:0xf bank_mask:0x3 bound_ctrl:1
	v_add_f32_dpp v38, v40, v40 row_ror:8 row_mask:0xf bank_mask:0xc bound_ctrl:1
	v_add_f32_dpp v39, v41, v41 row_ror:8 row_mask:0xf bank_mask:0xc bound_ctrl:1
	ds_read_b128 v[56:59], v2 offset:2304
	v_add_f32_dpp v38, v38, v38 row_half_mirror row_mask:0xf bank_mask:0x5 bound_ctrl:1
	v_add_f32_dpp v38, v39, v39 row_half_mirror row_mask:0xf bank_mask:0xa bound_ctrl:1
	ds_read_b128 v[60:63], v2 offset:2560
	ds_read_b128 v[64:67], v2 offset:2816
	v_add_f32_dpp v38, v38, v38 quad_perm:[1,0,3,2] row_mask:0xf bank_mask:0xf bound_ctrl:1
	ds_read_b128 v[68:71], v2 offset:3072
	ds_read_b64 v[72:73], v3 offset:13056
	v_add_f32_dpp v38, v38, v38 quad_perm:[2,3,0,1] row_mask:0xf bank_mask:0xf bound_ctrl:1
	ds_read_b128 v[76:79], v1 offset:14624
	v_cmp_gt_f32_e32 vcc, 0x2b8cbccc, v51
	v_fmac_f32_dpp v96, -v38, v51 row_newbcast:0 row_mask:0xf bank_mask:0xf bound_ctrl:1
	v_fmac_f32_dpp v97, -v38, v51 row_newbcast:4 row_mask:0xf bank_mask:0xf bound_ctrl:1
	v_rcp_f32_e32 v52, v51
	s_add_u32 s14, s14, 0x1000
	v_pk_mul_f32 v[44:45], v[96:97], v[100:101] op_sel:[0,1] op_sel_hi:[1,1]
	s_addc_u32 s15, s15, 0
	s_cbranch_vccnz .Lgd2_rare0_1
.Lgd2_back0_1:
	v_pk_mul_f32 v[46:47], v[44:45], v[52:53] op_sel_hi:[1,0]
	v_pk_mul_f32 v[48:49], v[44:45], v[102:103] op_sel_hi:[1,0]
	v_pk_fma_f32 v[6:7], v[80:81], v[46:47], v[6:7] op_sel_hi:[0,1,1]
	v_pk_fma_f32 v[8:9], v[82:83], v[46:47], v[8:9] op_sel_hi:[0,1,1]
	v_fmac_f32_dpp v48, v38, v51 row_newbcast:8 row_mask:0xf bank_mask:0xf bound_ctrl:1
	v_pk_fma_f32 v[10:11], v[84:85], v[46:47], v[10:11] op_sel_hi:[0,1,1]
	v_fmac_f32_dpp v49, v38, v51 row_newbcast:12 row_mask:0xf bank_mask:0xf bound_ctrl:1
	v_pk_fma_f32 v[12:13], v[86:87], v[46:47], v[12:13] op_sel_hi:[0,1,1]
	v_pk_fma_f32 v[14:15], v[88:89], v[46:47], v[14:15] op_sel_hi:[0,1,1]
	v_cvt_pk_bf16_f32 v54, v48, v49
	v_pk_fma_f32 v[16:17], v[90:91], v[46:47], v[16:17] op_sel_hi:[0,1,1]
	v_pk_fma_f32 v[18:19], v[92:93], v[46:47], v[18:19] op_sel_hi:[0,1,1]
	v_pk_fma_f32 v[20:21], v[94:95], v[46:47], v[20:21] op_sel_hi:[0,1,1]
	global_store_dword v154, v54, s[14:15] offset:-4096
	s_waitcnt lgkmcnt(5)
	v_pk_mul_f32 v[38:39], v[6:7], v[56:57] op_sel_hi:[1,0]
	v_pk_mul_f32 v[40:41], v[6:7], v[56:57] op_sel:[0,1] op_sel_hi:[1,1]
	v_pk_fma_f32 v[38:39], v[8:9], v[58:59], v[38:39] op_sel_hi:[1,0,1]
	v_pk_fma_f32 v[40:41], v[8:9], v[58:59], v[40:41] op_sel:[0,1,0] op_sel_hi:[1,1,1]
	s_waitcnt lgkmcnt(4)
	v_pk_fma_f32 v[38:39], v[10:11], v[60:61], v[38:39] op_sel_hi:[1,0,1]
	v_pk_fma_f32 v[40:41], v[10:11], v[60:61], v[40:41] op_sel:[0,1,0] op_sel_hi:[1,1,1]
	v_pk_fma_f32 v[38:39], v[12:13], v[62:63], v[38:39] op_sel_hi:[1,0,1]
	v_pk_fma_f32 v[40:41], v[12:13], v[62:63], v[40:41] op_sel:[0,1,0] op_sel_hi:[1,1,1]
	s_waitcnt lgkmcnt(3)
	v_pk_fma_f32 v[38:39], v[14:15], v[64:65], v[38:39] op_sel_hi:[1,0,1]
	v_pk_fma_f32 v[40:41], v[14:15], v[64:65], v[40:41] op_sel:[0,1,0] op_sel_hi:[1,1,1]
	v_pk_fma_f32 v[38:39], v[16:17], v[66:67], v[38:39] op_sel_hi:[1,0,1]
	v_pk_fma_f32 v[40:41], v[16:17], v[66:67], v[40:41] op_sel:[0,1,0] op_sel_hi:[1,1,1]
	s_waitcnt lgkmcnt(2)
	v_pk_fma_f32 v[38:39], v[18:19], v[68:69], v[38:39] op_sel_hi:[1,0,1]
	v_pk_fma_f32 v[40:41], v[18:19], v[68:69], v[40:41] op_sel:[0,1,0] op_sel_hi:[1,1,1]
	v_pk_fma_f32 v[38:39], v[20:21], v[70:71], v[38:39] op_sel_hi:[1,0,1]
	v_pk_fma_f32 v[40:41], v[20:21], v[70:71], v[40:41] op_sel:[0,1,0] op_sel_hi:[1,1,1]
	s_waitcnt lgkmcnt(0)
	v_mul_f32_e32 v50, v76, v51
	v_add_f32_dpp v38, v38, v38 row_ror:8 row_mask:0xf bank_mask:0x3 bound_ctrl:1
	v_add_f32_dpp v39, v39, v39 row_ror:8 row_mask:0xf bank_mask:0x3 bound_ctrl:1
	v_add_f32_dpp v38, v40, v40 row_ror:8 row_mask:0xf bank_mask:0xc bound_ctrl:1
	v_add_f32_dpp v39, v41, v41 row_ror:8 row_mask:0xf bank_mask:0xc bound_ctrl:1
	ds_read_b128 v[80:83], v2 offset:3328
	v_add_f32_dpp v38, v38, v38 row_half_mirror row_mask:0xf bank_mask:0x5 bound_ctrl:1
	v_add_f32_dpp v38, v39, v39 row_half_mirror row_mask:0xf bank_mask:0xa bound_ctrl:1
	ds_read_b128 v[84:87], v2 offset:3584
	ds_read_b128 v[88:91], v2 offset:3840
	v_add_f32_dpp v38, v38, v38 quad_perm:[1,0,3,2] row_mask:0xf bank_mask:0xf bound_ctrl:1
	ds_read_b128 v[92:95], v2 offset:4096
	ds_read_b64 v[96:97], v3 offset:13312
	v_add_f32_dpp v38, v38, v38 quad_perm:[2,3,0,1] row_mask:0xf bank_mask:0xf bound_ctrl:1
	ds_read_b128 v[100:103], v1 offset:14640
	v_cmp_gt_f32_e32 vcc, 0x2b8cbccc, v50
	v_fmac_f32_dpp v72, -v38, v50 row_newbcast:0 row_mask:0xf bank_mask:0xf bound_ctrl:1
	v_fmac_f32_dpp v73, -v38, v50 row_newbcast:4 row_mask:0xf bank_mask:0xf bound_ctrl:1
	v_rcp_f32_e32 v52, v50
	s_add_u32 s14, s14, 0x1000
	v_pk_mul_f32 v[44:45], v[72:73], v[76:77] op_sel:[0,1] op_sel_hi:[1,1]
	s_addc_u32 s15, s15, 0
	s_cbranch_vccnz .Lgd2_rare0_2
.Lgd2_back0_2:
	v_pk_mul_f32 v[46:47], v[44:45], v[52:53] op_sel_hi:[1,0]
	v_pk_mul_f32 v[48:49], v[44:45], v[78:79] op_sel_hi:[1,0]
	v_pk_fma_f32 v[6:7], v[56:57], v[46:47], v[6:7] op_sel_hi:[0,1,1]
	v_pk_fma_f32 v[8:9], v[58:59], v[46:47], v[8:9] op_sel_hi:[0,1,1]
	v_fmac_f32_dpp v48, v38, v50 row_newbcast:8 row_mask:0xf bank_mask:0xf bound_ctrl:1
	v_pk_fma_f32 v[10:11], v[60:61], v[46:47], v[10:11] op_sel_hi:[0,1,1]
	v_fmac_f32_dpp v49, v38, v50 row_newbcast:12 row_mask:0xf bank_mask:0xf bound_ctrl:1
	v_pk_fma_f32 v[12:13], v[62:63], v[46:47], v[12:13] op_sel_hi:[0,1,1]
	v_pk_fma_f32 v[14:15], v[64:65], v[46:47], v[14:15] op_sel_hi:[0,1,1]
	v_cvt_pk_bf16_f32 v54, v48, v49
	v_pk_fma_f32 v[16:17], v[66:67], v[46:47], v[16:17] op_sel_hi:[0,1,1]
	v_pk_fma_f32 v[18:19], v[68:69], v[46:47], v[18:19] op_sel_hi:[0,1,1]
	v_pk_fma_f32 v[20:21], v[70:71], v[46:47], v[20:21] op_sel_hi:[0,1,1]
	global_store_dword v154, v54, s[14:15] offset:-4096
	s_waitcnt lgkmcnt(5)
	v_pk_mul_f32 v[38:39], v[6:7], v[80:81] op_sel_hi:[1,0]
	v_pk_mul_f32 v[40:41], v[6:7], v[80:81] op_sel:[0,1] op_sel_hi:[1,1]
	v_pk_fma_f32 v[38:39], v[8:9], v[82:83], v[38:39] op_sel_hi:[1,0,1]
	v_pk_fma_f32 v[40:41], v[8:9], v[82:83], v[40:41] op_sel:[0,1,0] op_sel_hi:[1,1,1]
	s_waitcnt lgkmcnt(4)
	v_pk_fma_f32 v[38:39], v[10:11], v[84:85], v[38:39] op_sel_hi:[1,0,1]
	v_pk_fma_f32 v[40:41], v[10:11], v[84:85], v[40:41] op_sel:[0,1,0] op_sel_hi:[1,1,1]
	v_pk_fma_f32 v[38:39], v[12:13], v[86:87], v[38:39] op_sel_hi:[1,0,1]
	v_pk_fma_f32 v[40:41], v[12:13], v[86:87], v[40:41] op_sel:[0,1,0] op_sel_hi:[1,1,1]
	s_waitcnt lgkmcnt(3)
	v_pk_fma_f32 v[38:39], v[14:15], v[88:89], v[38:39] op_sel_hi:[1,0,1]
	v_pk_fma_f32 v[40:41], v[14:15], v[88:89], v[40:41] op_sel:[0,1,0] op_sel_hi:[1,1,1]
	v_pk_fma_f32 v[38:39], v[16:17], v[90:91], v[38:39] op_sel_hi:[1,0,1]
	v_pk_fma_f32 v[40:41], v[16:17], v[90:91], v[40:41] op_sel:[0,1,0] op_sel_hi:[1,1,1]
	s_waitcnt lgkmcnt(2)
	v_pk_fma_f32 v[38:39], v[18:19], v[92:93], v[38:39] op_sel_hi:[1,0,1]
	v_pk_fma_f32 v[40:41], v[18:19], v[92:93], v[40:41] op_sel:[0,1,0] op_sel_hi:[1,1,1]
	v_pk_fma_f32 v[38:39], v[20:21], v[94:95], v[38:39] op_sel_hi:[1,0,1]
	v_pk_fma_f32 v[40:41], v[20:21], v[94:95], v[40:41] op_sel:[0,1,0] op_sel_hi:[1,1,1]
	s_waitcnt lgkmcnt(0)
	v_mul_f32_e32 v51, v100, v50
	v_add_f32_dpp v38, v38, v38 row_ror:8 row_mask:0xf bank_mask:0x3 bound_ctrl:1
	v_add_f32_dpp v39, v39, v39 row_ror:8 row_mask:0xf bank_mask:0x3 bound_ctrl:1
	v_add_f32_dpp v38, v40, v40 row_ror:8 row_mask:0xf bank_mask:0xc bound_ctrl:1
	v_add_f32_dpp v39, v41, v41 row_ror:8 row_mask:0xf bank_mask:0xc bound_ctrl:1
	ds_read_b128 v[56:59], v2 offset:4352
	v_add_f32_dpp v38, v38, v38 row_half_mirror row_mask:0xf bank_mask:0x5 bound_ctrl:1
	v_add_f32_dpp v38, v39, v39 row_half_mirror row_mask:0xf bank_mask:0xa bound_ctrl:1
	ds_read_b128 v[60:63], v2 offset:4608
	ds_read_b128 v[64:67], v2 offset:4864
	v_add_f32_dpp v38, v38, v38 quad_perm:[1,0,3,2] row_mask:0xf bank_mask:0xf bound_ctrl:1
	ds_read_b128 v[68:71], v2 offset:5120
	ds_read_b64 v[72:73], v3 offset:13568
	v_add_f32_dpp v38, v38, v38 quad_perm:[2,3,0,1] row_mask:0xf bank_mask:0xf bound_ctrl:1
	ds_read_b128 v[76:79], v1 offset:14656
	v_cmp_gt_f32_e32 vcc, 0x2b8cbccc, v51
	v_fmac_f32_dpp v96, -v38, v51 row_newbcast:0 row_mask:0xf bank_mask:0xf bound_ctrl:1
	v_fmac_f32_dpp v97, -v38, v51 row_newbcast:4 row_mask:0xf bank_mask:0xf bound_ctrl:1
	v_rcp_f32_e32 v52, v51
	s_add_u32 s14, s14, 0x1000
	v_pk_mul_f32 v[44:45], v[96:97], v[100:101] op_sel:[0,1] op_sel_hi:[1,1]
	s_addc_u32 s15, s15, 0
	s_cbranch_vccnz .Lgd2_rare0_3
.Lgd2_back0_3:
	v_pk_mul_f32 v[46:47], v[44:45], v[52:53] op_sel_hi:[1,0]
	v_pk_mul_f32 v[48:49], v[44:45], v[102:103] op_sel_hi:[1,0]
	v_pk_fma_f32 v[6:7], v[80:81], v[46:47], v[6:7] op_sel_hi:[0,1,1]
	v_pk_fma_f32 v[8:9], v[82:83], v[46:47], v[8:9] op_sel_hi:[0,1,1]
	v_fmac_f32_dpp v48, v38, v51 row_newbcast:8 row_mask:0xf bank_mask:0xf bound_ctrl:1
	v_pk_fma_f32 v[10:11], v[84:85], v[46:47], v[10:11] op_sel_hi:[0,1,1]
	v_fmac_f32_dpp v49, v38, v51 row_newbcast:12 row_mask:0xf bank_mask:0xf bound_ctrl:1
	v_pk_fma_f32 v[12:13], v[86:87], v[46:47], v[12:13] op_sel_hi:[0,1,1]
	v_pk_fma_f32 v[14:15], v[88:89], v[46:47], v[14:15] op_sel_hi:[0,1,1]
	v_cvt_pk_bf16_f32 v54, v48, v49
	v_pk_fma_f32 v[16:17], v[90:91], v[46:47], v[16:17] op_sel_hi:[0,1,1]
	v_pk_fma_f32 v[18:19], v[92:93], v[46:47], v[18:19] op_sel_hi:[0,1,1]
	v_pk_fma_f32 v[20:21], v[94:95], v[46:47], v[20:21] op_sel_hi:[0,1,1]
	global_store_dword v154, v54, s[14:15] offset:-4096
	s_waitcnt lgkmcnt(5)
	v_pk_mul_f32 v[38:39], v[6:7], v[56:57] op_sel_hi:[1,0]
	v_pk_mul_f32 v[40:41], v[6:7], v[56:57] op_sel:[0,1] op_sel_hi:[1,1]
	v_pk_fma_f32 v[38:39], v[8:9], v[58:59], v[38:39] op_sel_hi:[1,0,1]
	v_pk_fma_f32 v[40:41], v[8:9], v[58:59], v[40:41] op_sel:[0,1,0] op_sel_hi:[1,1,1]
	s_waitcnt lgkmcnt(4)
	v_pk_fma_f32 v[38:39], v[10:11], v[60:61], v[38:39] op_sel_hi:[1,0,1]
	v_pk_fma_f32 v[40:41], v[10:11], v[60:61], v[40:41] op_sel:[0,1,0] op_sel_hi:[1,1,1]
	v_pk_fma_f32 v[38:39], v[12:13], v[62:63], v[38:39] op_sel_hi:[1,0,1]
	v_pk_fma_f32 v[40:41], v[12:13], v[62:63], v[40:41] op_sel:[0,1,0] op_sel_hi:[1,1,1]
	s_waitcnt lgkmcnt(3)
	v_pk_fma_f32 v[38:39], v[14:15], v[64:65], v[38:39] op_sel_hi:[1,0,1]
	v_pk_fma_f32 v[40:41], v[14:15], v[64:65], v[40:41] op_sel:[0,1,0] op_sel_hi:[1,1,1]
	v_pk_fma_f32 v[38:39], v[16:17], v[66:67], v[38:39] op_sel_hi:[1,0,1]
	v_pk_fma_f32 v[40:41], v[16:17], v[66:67], v[40:41] op_sel:[0,1,0] op_sel_hi:[1,1,1]
	s_waitcnt lgkmcnt(2)
	v_pk_fma_f32 v[38:39], v[18:19], v[68:69], v[38:39] op_sel_hi:[1,0,1]
	v_pk_fma_f32 v[40:41], v[18:19], v[68:69], v[40:41] op_sel:[0,1,0] op_sel_hi:[1,1,1]
	v_pk_fma_f32 v[38:39], v[20:21], v[70:71], v[38:39] op_sel_hi:[1,0,1]
	v_pk_fma_f32 v[40:41], v[20:21], v[70:71], v[40:41] op_sel:[0,1,0] op_sel_hi:[1,1,1]
	s_waitcnt lgkmcnt(0)
	v_mul_f32_e32 v50, v76, v51
	v_add_f32_dpp v38, v38, v38 row_ror:8 row_mask:0xf bank_mask:0x3 bound_ctrl:1
	v_add_f32_dpp v39, v39, v39 row_ror:8 row_mask:0xf bank_mask:0x3 bound_ctrl:1
	v_add_f32_dpp v38, v40, v40 row_ror:8 row_mask:0xf bank_mask:0xc bound_ctrl:1
	v_add_f32_dpp v39, v41, v41 row_ror:8 row_mask:0xf bank_mask:0xc bound_ctrl:1
	ds_read_b128 v[80:83], v2 offset:5376
	v_add_f32_dpp v38, v38, v38 row_half_mirror row_mask:0xf bank_mask:0x5 bound_ctrl:1
	v_add_f32_dpp v38, v39, v39 row_half_mirror row_mask:0xf bank_mask:0xa bound_ctrl:1
	ds_read_b128 v[84:87], v2 offset:5632
	ds_read_b128 v[88:91], v2 offset:5888
	v_add_f32_dpp v38, v38, v38 quad_perm:[1,0,3,2] row_mask:0xf bank_mask:0xf bound_ctrl:1
	ds_read_b128 v[92:95], v2 offset:6144
	ds_read_b64 v[96:97], v3 offset:13824
	v_add_f32_dpp v38, v38, v38 quad_perm:[2,3,0,1] row_mask:0xf bank_mask:0xf bound_ctrl:1
	ds_read_b128 v[100:103], v1 offset:14672
	v_cmp_gt_f32_e32 vcc, 0x2b8cbccc, v50
	v_fmac_f32_dpp v72, -v38, v50 row_newbcast:0 row_mask:0xf bank_mask:0xf bound_ctrl:1
	v_fmac_f32_dpp v73, -v38, v50 row_newbcast:4 row_mask:0xf bank_mask:0xf bound_ctrl:1
	v_rcp_f32_e32 v52, v50
	s_add_u32 s14, s14, 0x1000
	v_pk_mul_f32 v[44:45], v[72:73], v[76:77] op_sel:[0,1] op_sel_hi:[1,1]
	s_addc_u32 s15, s15, 0
	s_cbranch_vccnz .Lgd2_rare0_4
.Lgd2_back0_4:
	v_pk_mul_f32 v[46:47], v[44:45], v[52:53] op_sel_hi:[1,0]
	v_pk_mul_f32 v[48:49], v[44:45], v[78:79] op_sel_hi:[1,0]
	v_pk_fma_f32 v[6:7], v[56:57], v[46:47], v[6:7] op_sel_hi:[0,1,1]
	v_pk_fma_f32 v[8:9], v[58:59], v[46:47], v[8:9] op_sel_hi:[0,1,1]
	v_fmac_f32_dpp v48, v38, v50 row_newbcast:8 row_mask:0xf bank_mask:0xf bound_ctrl:1
	v_pk_fma_f32 v[10:11], v[60:61], v[46:47], v[10:11] op_sel_hi:[0,1,1]
	v_fmac_f32_dpp v49, v38, v50 row_newbcast:12 row_mask:0xf bank_mask:0xf bound_ctrl:1
	v_pk_fma_f32 v[12:13], v[62:63], v[46:47], v[12:13] op_sel_hi:[0,1,1]
	v_pk_fma_f32 v[14:15], v[64:65], v[46:47], v[14:15] op_sel_hi:[0,1,1]
	v_cvt_pk_bf16_f32 v54, v48, v49
	v_pk_fma_f32 v[16:17], v[66:67], v[46:47], v[16:17] op_sel_hi:[0,1,1]
	v_pk_fma_f32 v[18:19], v[68:69], v[46:47], v[18:19] op_sel_hi:[0,1,1]
	v_pk_fma_f32 v[20:21], v[70:71], v[46:47], v[20:21] op_sel_hi:[0,1,1]
	global_store_dword v154, v54, s[14:15] offset:-4096
	s_waitcnt lgkmcnt(5)
	v_pk_mul_f32 v[38:39], v[6:7], v[80:81] op_sel_hi:[1,0]
	v_pk_mul_f32 v[40:41], v[6:7], v[80:81] op_sel:[0,1] op_sel_hi:[1,1]
	v_pk_fma_f32 v[38:39], v[8:9], v[82:83], v[38:39] op_sel_hi:[1,0,1]
	v_pk_fma_f32 v[40:41], v[8:9], v[82:83], v[40:41] op_sel:[0,1,0] op_sel_hi:[1,1,1]
	s_waitcnt lgkmcnt(4)
	v_pk_fma_f32 v[38:39], v[10:11], v[84:85], v[38:39] op_sel_hi:[1,0,1]
	v_pk_fma_f32 v[40:41], v[10:11], v[84:85], v[40:41] op_sel:[0,1,0] op_sel_hi:[1,1,1]
	v_pk_fma_f32 v[38:39], v[12:13], v[86:87], v[38:39] op_sel_hi:[1,0,1]
	v_pk_fma_f32 v[40:41], v[12:13], v[86:87], v[40:41] op_sel:[0,1,0] op_sel_hi:[1,1,1]
	s_waitcnt lgkmcnt(3)
	v_pk_fma_f32 v[38:39], v[14:15], v[88:89], v[38:39] op_sel_hi:[1,0,1]
	v_pk_fma_f32 v[40:41], v[14:15], v[88:89], v[40:41] op_sel:[0,1,0] op_sel_hi:[1,1,1]
	v_pk_fma_f32 v[38:39], v[16:17], v[90:91], v[38:39] op_sel_hi:[1,0,1]
	v_pk_fma_f32 v[40:41], v[16:17], v[90:91], v[40:41] op_sel:[0,1,0] op_sel_hi:[1,1,1]
	s_waitcnt lgkmcnt(2)
	v_pk_fma_f32 v[38:39], v[18:19], v[92:93], v[38:39] op_sel_hi:[1,0,1]
	v_pk_fma_f32 v[40:41], v[18:19], v[92:93], v[40:41] op_sel:[0,1,0] op_sel_hi:[1,1,1]
	v_pk_fma_f32 v[38:39], v[20:21], v[94:95], v[38:39] op_sel_hi:[1,0,1]
	v_pk_fma_f32 v[40:41], v[20:21], v[94:95], v[40:41] op_sel:[0,1,0] op_sel_hi:[1,1,1]
	s_waitcnt lgkmcnt(0)
	v_mul_f32_e32 v51, v100, v50
	v_add_f32_dpp v38, v38, v38 row_ror:8 row_mask:0xf bank_mask:0x3 bound_ctrl:1
	v_add_f32_dpp v39, v39, v39 row_ror:8 row_mask:0xf bank_mask:0x3 bound_ctrl:1
	v_add_f32_dpp v38, v40, v40 row_ror:8 row_mask:0xf bank_mask:0xc bound_ctrl:1
	v_add_f32_dpp v39, v41, v41 row_ror:8 row_mask:0xf bank_mask:0xc bound_ctrl:1
	ds_read_b128 v[56:59], v2 offset:6400
	v_add_f32_dpp v38, v38, v38 row_half_mirror row_mask:0xf bank_mask:0x5 bound_ctrl:1
	v_add_f32_dpp v38, v39, v39 row_half_mirror row_mask:0xf bank_mask:0xa bound_ctrl:1
	ds_read_b128 v[60:63], v2 offset:6656
	ds_read_b128 v[64:67], v2 offset:6912
	v_add_f32_dpp v38, v38, v38 quad_perm:[1,0,3,2] row_mask:0xf bank_mask:0xf bound_ctrl:1
	ds_read_b128 v[68:71], v2 offset:7168
	ds_read_b64 v[72:73], v3 offset:14080
	v_add_f32_dpp v38, v38, v38 quad_perm:[2,3,0,1] row_mask:0xf bank_mask:0xf bound_ctrl:1
	ds_read_b128 v[76:79], v1 offset:14688
	v_cmp_gt_f32_e32 vcc, 0x2b8cbccc, v51
	v_fmac_f32_dpp v96, -v38, v51 row_newbcast:0 row_mask:0xf bank_mask:0xf bound_ctrl:1
	v_fmac_f32_dpp v97, -v38, v51 row_newbcast:4 row_mask:0xf bank_mask:0xf bound_ctrl:1
	v_rcp_f32_e32 v52, v51
	s_add_u32 s14, s14, 0x1000
	v_pk_mul_f32 v[44:45], v[96:97], v[100:101] op_sel:[0,1] op_sel_hi:[1,1]
	s_addc_u32 s15, s15, 0
	s_cbranch_vccnz .Lgd2_rare0_5
.Lgd2_back0_5:
	v_pk_mul_f32 v[46:47], v[44:45], v[52:53] op_sel_hi:[1,0]
	v_pk_mul_f32 v[48:49], v[44:45], v[102:103] op_sel_hi:[1,0]
	v_pk_fma_f32 v[6:7], v[80:81], v[46:47], v[6:7] op_sel_hi:[0,1,1]
	v_pk_fma_f32 v[8:9], v[82:83], v[46:47], v[8:9] op_sel_hi:[0,1,1]
	v_fmac_f32_dpp v48, v38, v51 row_newbcast:8 row_mask:0xf bank_mask:0xf bound_ctrl:1
	v_pk_fma_f32 v[10:11], v[84:85], v[46:47], v[10:11] op_sel_hi:[0,1,1]
	v_fmac_f32_dpp v49, v38, v51 row_newbcast:12 row_mask:0xf bank_mask:0xf bound_ctrl:1
	v_pk_fma_f32 v[12:13], v[86:87], v[46:47], v[12:13] op_sel_hi:[0,1,1]
	v_pk_fma_f32 v[14:15], v[88:89], v[46:47], v[14:15] op_sel_hi:[0,1,1]
	v_cvt_pk_bf16_f32 v54, v48, v49
	v_pk_fma_f32 v[16:17], v[90:91], v[46:47], v[16:17] op_sel_hi:[0,1,1]
	v_pk_fma_f32 v[18:19], v[92:93], v[46:47], v[18:19] op_sel_hi:[0,1,1]
	v_pk_fma_f32 v[20:21], v[94:95], v[46:47], v[20:21] op_sel_hi:[0,1,1]
	global_store_dword v154, v54, s[14:15] offset:-4096
	s_waitcnt lgkmcnt(5)
	v_pk_mul_f32 v[38:39], v[6:7], v[56:57] op_sel_hi:[1,0]
	v_pk_mul_f32 v[40:41], v[6:7], v[56:57] op_sel:[0,1] op_sel_hi:[1,1]
	v_pk_fma_f32 v[38:39], v[8:9], v[58:59], v[38:39] op_sel_hi:[1,0,1]
	v_pk_fma_f32 v[40:41], v[8:9], v[58:59], v[40:41] op_sel:[0,1,0] op_sel_hi:[1,1,1]
	s_waitcnt lgkmcnt(4)
	v_pk_fma_f32 v[38:39], v[10:11], v[60:61], v[38:39] op_sel_hi:[1,0,1]
	v_pk_fma_f32 v[40:41], v[10:11], v[60:61], v[40:41] op_sel:[0,1,0] op_sel_hi:[1,1,1]
	v_pk_fma_f32 v[38:39], v[12:13], v[62:63], v[38:39] op_sel_hi:[1,0,1]
	v_pk_fma_f32 v[40:41], v[12:13], v[62:63], v[40:41] op_sel:[0,1,0] op_sel_hi:[1,1,1]
	s_waitcnt lgkmcnt(3)
	v_pk_fma_f32 v[38:39], v[14:15], v[64:65], v[38:39] op_sel_hi:[1,0,1]
	v_pk_fma_f32 v[40:41], v[14:15], v[64:65], v[40:41] op_sel:[0,1,0] op_sel_hi:[1,1,1]
	v_pk_fma_f32 v[38:39], v[16:17], v[66:67], v[38:39] op_sel_hi:[1,0,1]
	v_pk_fma_f32 v[40:41], v[16:17], v[66:67], v[40:41] op_sel:[0,1,0] op_sel_hi:[1,1,1]
	s_waitcnt lgkmcnt(2)
	v_pk_fma_f32 v[38:39], v[18:19], v[68:69], v[38:39] op_sel_hi:[1,0,1]
	v_pk_fma_f32 v[40:41], v[18:19], v[68:69], v[40:41] op_sel:[0,1,0] op_sel_hi:[1,1,1]
	v_pk_fma_f32 v[38:39], v[20:21], v[70:71], v[38:39] op_sel_hi:[1,0,1]
	v_pk_fma_f32 v[40:41], v[20:21], v[70:71], v[40:41] op_sel:[0,1,0] op_sel_hi:[1,1,1]
	s_waitcnt lgkmcnt(0)
	v_mul_f32_e32 v50, v76, v51
	v_add_f32_dpp v38, v38, v38 row_ror:8 row_mask:0xf bank_mask:0x3 bound_ctrl:1
	v_add_f32_dpp v39, v39, v39 row_ror:8 row_mask:0xf bank_mask:0x3 bound_ctrl:1
	v_add_f32_dpp v38, v40, v40 row_ror:8 row_mask:0xf bank_mask:0xc bound_ctrl:1
	v_add_f32_dpp v39, v41, v41 row_ror:8 row_mask:0xf bank_mask:0xc bound_ctrl:1
	ds_read_b128 v[80:83], v2 offset:7424
	v_add_f32_dpp v38, v38, v38 row_half_mirror row_mask:0xf bank_mask:0x5 bound_ctrl:1
	v_add_f32_dpp v38, v39, v39 row_half_mirror row_mask:0xf bank_mask:0xa bound_ctrl:1
	ds_read_b128 v[84:87], v2 offset:7680
	ds_read_b128 v[88:91], v2 offset:7936
	v_add_f32_dpp v38, v38, v38 quad_perm:[1,0,3,2] row_mask:0xf bank_mask:0xf bound_ctrl:1
	ds_read_b128 v[92:95], v2 offset:8192
	ds_read_b64 v[96:97], v3 offset:14336
	v_add_f32_dpp v38, v38, v38 quad_perm:[2,3,0,1] row_mask:0xf bank_mask:0xf bound_ctrl:1
	ds_read_b128 v[100:103], v1 offset:14704
	v_cmp_gt_f32_e32 vcc, 0x2b8cbccc, v50
	v_fmac_f32_dpp v72, -v38, v50 row_newbcast:0 row_mask:0xf bank_mask:0xf bound_ctrl:1
	v_fmac_f32_dpp v73, -v38, v50 row_newbcast:4 row_mask:0xf bank_mask:0xf bound_ctrl:1
	v_rcp_f32_e32 v52, v50
	s_add_u32 s14, s14, 0x1000
	v_pk_mul_f32 v[44:45], v[72:73], v[76:77] op_sel:[0,1] op_sel_hi:[1,1]
	s_addc_u32 s15, s15, 0
	s_cbranch_vccnz .Lgd2_rare0_6
.Lgd2_back0_6:
	v_pk_mul_f32 v[46:47], v[44:45], v[52:53] op_sel_hi:[1,0]
	v_pk_mul_f32 v[48:49], v[44:45], v[78:79] op_sel_hi:[1,0]
	v_pk_fma_f32 v[6:7], v[56:57], v[46:47], v[6:7] op_sel_hi:[0,1,1]
	v_pk_fma_f32 v[8:9], v[58:59], v[46:47], v[8:9] op_sel_hi:[0,1,1]
	v_fmac_f32_dpp v48, v38, v50 row_newbcast:8 row_mask:0xf bank_mask:0xf bound_ctrl:1
	v_pk_fma_f32 v[10:11], v[60:61], v[46:47], v[10:11] op_sel_hi:[0,1,1]
	v_fmac_f32_dpp v49, v38, v50 row_newbcast:12 row_mask:0xf bank_mask:0xf bound_ctrl:1
	v_pk_fma_f32 v[12:13], v[62:63], v[46:47], v[12:13] op_sel_hi:[0,1,1]
	v_pk_fma_f32 v[14:15], v[64:65], v[46:47], v[14:15] op_sel_hi:[0,1,1]
	v_cvt_pk_bf16_f32 v54, v48, v49
	v_pk_fma_f32 v[16:17], v[66:67], v[46:47], v[16:17] op_sel_hi:[0,1,1]
	v_pk_fma_f32 v[18:19], v[68:69], v[46:47], v[18:19] op_sel_hi:[0,1,1]
	v_pk_fma_f32 v[20:21], v[70:71], v[46:47], v[20:21] op_sel_hi:[0,1,1]
	global_store_dword v154, v54, s[14:15] offset:-4096
	s_waitcnt lgkmcnt(5)
	v_pk_mul_f32 v[38:39], v[6:7], v[80:81] op_sel_hi:[1,0]
	v_pk_mul_f32 v[40:41], v[6:7], v[80:81] op_sel:[0,1] op_sel_hi:[1,1]
	v_pk_fma_f32 v[38:39], v[8:9], v[82:83], v[38:39] op_sel_hi:[1,0,1]
	v_pk_fma_f32 v[40:41], v[8:9], v[82:83], v[40:41] op_sel:[0,1,0] op_sel_hi:[1,1,1]
	s_waitcnt lgkmcnt(4)
	v_pk_fma_f32 v[38:39], v[10:11], v[84:85], v[38:39] op_sel_hi:[1,0,1]
	v_pk_fma_f32 v[40:41], v[10:11], v[84:85], v[40:41] op_sel:[0,1,0] op_sel_hi:[1,1,1]
	v_pk_fma_f32 v[38:39], v[12:13], v[86:87], v[38:39] op_sel_hi:[1,0,1]
	v_pk_fma_f32 v[40:41], v[12:13], v[86:87], v[40:41] op_sel:[0,1,0] op_sel_hi:[1,1,1]
	s_waitcnt lgkmcnt(3)
	v_pk_fma_f32 v[38:39], v[14:15], v[88:89], v[38:39] op_sel_hi:[1,0,1]
	v_pk_fma_f32 v[40:41], v[14:15], v[88:89], v[40:41] op_sel:[0,1,0] op_sel_hi:[1,1,1]
	v_pk_fma_f32 v[38:39], v[16:17], v[90:91], v[38:39] op_sel_hi:[1,0,1]
	v_pk_fma_f32 v[40:41], v[16:17], v[90:91], v[40:41] op_sel:[0,1,0] op_sel_hi:[1,1,1]
	s_waitcnt lgkmcnt(2)
	v_pk_fma_f32 v[38:39], v[18:19], v[92:93], v[38:39] op_sel_hi:[1,0,1]
	v_pk_fma_f32 v[40:41], v[18:19], v[92:93], v[40:41] op_sel:[0,1,0] op_sel_hi:[1,1,1]
	v_pk_fma_f32 v[38:39], v[20:21], v[94:95], v[38:39] op_sel_hi:[1,0,1]
	v_pk_fma_f32 v[40:41], v[20:21], v[94:95], v[40:41] op_sel:[0,1,0] op_sel_hi:[1,1,1]
	s_waitcnt lgkmcnt(0)
	v_mul_f32_e32 v51, v100, v50
	v_add_f32_dpp v38, v38, v38 row_ror:8 row_mask:0xf bank_mask:0x3 bound_ctrl:1
	v_add_f32_dpp v39, v39, v39 row_ror:8 row_mask:0xf bank_mask:0x3 bound_ctrl:1
	v_add_f32_dpp v38, v40, v40 row_ror:8 row_mask:0xf bank_mask:0xc bound_ctrl:1
	v_add_f32_dpp v39, v41, v41 row_ror:8 row_mask:0xf bank_mask:0xc bound_ctrl:1
	ds_read_b128 v[56:59], v2 offset:16640
	v_add_f32_dpp v38, v38, v38 row_half_mirror row_mask:0xf bank_mask:0x5 bound_ctrl:1
	v_add_f32_dpp v38, v39, v39 row_half_mirror row_mask:0xf bank_mask:0xa bound_ctrl:1
	ds_read_b128 v[60:63], v2 offset:16896
	ds_read_b128 v[64:67], v2 offset:17152
	v_add_f32_dpp v38, v38, v38 quad_perm:[1,0,3,2] row_mask:0xf bank_mask:0xf bound_ctrl:1
	ds_read_b128 v[68:71], v2 offset:17408
	ds_read_b64 v[72:73], v3 offset:28928
	v_add_f32_dpp v38, v38, v38 quad_perm:[2,3,0,1] row_mask:0xf bank_mask:0xf bound_ctrl:1
	ds_read_b128 v[76:79], v1 offset:30976
	v_cmp_gt_f32_e32 vcc, 0x2b8cbccc, v51
	v_fmac_f32_dpp v96, -v38, v51 row_newbcast:0 row_mask:0xf bank_mask:0xf bound_ctrl:1
	v_fmac_f32_dpp v97, -v38, v51 row_newbcast:4 row_mask:0xf bank_mask:0xf bound_ctrl:1
	v_rcp_f32_e32 v52, v51
	s_add_u32 s14, s14, 0x1000
	v_pk_mul_f32 v[44:45], v[96:97], v[100:101] op_sel:[0,1] op_sel_hi:[1,1]
	s_addc_u32 s15, s15, 0
	s_cbranch_vccnz .Lgd2_rare0_7
.Lgd2_back0_7:
	v_pk_mul_f32 v[46:47], v[44:45], v[52:53] op_sel_hi:[1,0]
	v_pk_mul_f32 v[48:49], v[44:45], v[102:103] op_sel_hi:[1,0]
	v_pk_fma_f32 v[6:7], v[80:81], v[46:47], v[6:7] op_sel_hi:[0,1,1]
	v_pk_fma_f32 v[8:9], v[82:83], v[46:47], v[8:9] op_sel_hi:[0,1,1]
	v_fmac_f32_dpp v48, v38, v51 row_newbcast:8 row_mask:0xf bank_mask:0xf bound_ctrl:1
	v_pk_fma_f32 v[10:11], v[84:85], v[46:47], v[10:11] op_sel_hi:[0,1,1]
	v_fmac_f32_dpp v49, v38, v51 row_newbcast:12 row_mask:0xf bank_mask:0xf bound_ctrl:1
	v_pk_fma_f32 v[12:13], v[86:87], v[46:47], v[12:13] op_sel_hi:[0,1,1]
	v_pk_fma_f32 v[14:15], v[88:89], v[46:47], v[14:15] op_sel_hi:[0,1,1]
	v_cvt_pk_bf16_f32 v54, v48, v49
	v_pk_fma_f32 v[16:17], v[90:91], v[46:47], v[16:17] op_sel_hi:[0,1,1]
	v_pk_fma_f32 v[18:19], v[92:93], v[46:47], v[18:19] op_sel_hi:[0,1,1]
	v_pk_fma_f32 v[20:21], v[94:95], v[46:47], v[20:21] op_sel_hi:[0,1,1]
	global_store_dword v154, v54, s[14:15] offset:-4096
	s_waitcnt vmcnt(8)
	v_lshlrev_b32_e32 v116, 16, v108
	v_lshlrev_b32_e32 v117, 16, v109
	v_and_b32_e32 v118, s17, v108
	v_and_b32_e32 v119, s17, v109
	v_lshlrev_b32_e32 v120, 16, v110
	v_and_b32_e32 v121, s17, v110
	v_lshlrev_b32_e32 v122, 16, v111
	v_and_b32_e32 v123, s17, v111
	v_lshlrev_b32_e32 v124, 16, v112
	v_and_b32_e32 v125, s17, v112
	ds_write_b128 v32, v[116:119] offset:33024
	ds_write_b64 v33, v[120:121] offset:33024
	ds_write_b64 v34, v[122:123] offset:33024
	ds_write_b64 v34, v[124:125] offset:33152
	ds_write_b32 v35, v113 offset:33024
	s_add_i32 s16, s16, 8
	s_waitcnt lgkmcnt(0)
	s_barrier
	s_cmpk_lt_u32 s16, 0x800
	s_cbranch_scc0 .Lgd2_done
	global_load_dword v108, v36, s[8:9]
	global_load_dword v109, v36, s[8:9] offset:-2048
	global_load_dword v111, v104, s[8:9] offset:2048
	global_load_dword v110, v37, s[10:11]
	global_load_dword v112, v105, s[10:11]
	global_load_dword v113, v106, s[12:13]
	s_add_u32 s8, s8, 0xc000
	s_addc_u32 s9, s9, 0
	s_add_u32 s10, s10, 0x20000
	s_addc_u32 s11, s11, 0
	s_add_u32 s12, s12, 0x400
	s_addc_u32 s13, s13, 0
	s_waitcnt lgkmcnt(5)
	v_pk_mul_f32 v[38:39], v[6:7], v[56:57] op_sel_hi:[1,0]
	v_pk_mul_f32 v[40:41], v[6:7], v[56:57] op_sel:[0,1] op_sel_hi:[1,1]
	v_pk_fma_f32 v[38:39], v[8:9], v[58:59], v[38:39] op_sel_hi:[1,0,1]
	v_pk_fma_f32 v[40:41], v[8:9], v[58:59], v[40:41] op_sel:[0,1,0] op_sel_hi:[1,1,1]
	s_waitcnt lgkmcnt(4)
	v_pk_fma_f32 v[38:39], v[10:11], v[60:61], v[38:39] op_sel_hi:[1,0,1]
	v_pk_fma_f32 v[40:41], v[10:11], v[60:61], v[40:41] op_sel:[0,1,0] op_sel_hi:[1,1,1]
	v_pk_fma_f32 v[38:39], v[12:13], v[62:63], v[38:39] op_sel_hi:[1,0,1]
	v_pk_fma_f32 v[40:41], v[12:13], v[62:63], v[40:41] op_sel:[0,1,0] op_sel_hi:[1,1,1]
	s_waitcnt lgkmcnt(3)
	v_pk_fma_f32 v[38:39], v[14:15], v[64:65], v[38:39] op_sel_hi:[1,0,1]
	v_pk_fma_f32 v[40:41], v[14:15], v[64:65], v[40:41] op_sel:[0,1,0] op_sel_hi:[1,1,1]
	v_pk_fma_f32 v[38:39], v[16:17], v[66:67], v[38:39] op_sel_hi:[1,0,1]
	v_pk_fma_f32 v[40:41], v[16:17], v[66:67], v[40:41] op_sel:[0,1,0] op_sel_hi:[1,1,1]
	s_waitcnt lgkmcnt(2)
	v_pk_fma_f32 v[38:39], v[18:19], v[68:69], v[38:39] op_sel_hi:[1,0,1]
	v_pk_fma_f32 v[40:41], v[18:19], v[68:69], v[40:41] op_sel:[0,1,0] op_sel_hi:[1,1,1]
	v_pk_fma_f32 v[38:39], v[20:21], v[70:71], v[38:39] op_sel_hi:[1,0,1]
	v_pk_fma_f32 v[40:41], v[20:21], v[70:71], v[40:41] op_sel:[0,1,0] op_sel_hi:[1,1,1]
	s_waitcnt lgkmcnt(0)
	v_mul_f32_e32 v50, v76, v51
	v_add_f32_dpp v38, v38, v38 row_ror:8 row_mask:0xf bank_mask:0x3 bound_ctrl:1
	v_add_f32_dpp v39, v39, v39 row_ror:8 row_mask:0xf bank_mask:0x3 bound_ctrl:1
	v_add_f32_dpp v38, v40, v40 row_ror:8 row_mask:0xf bank_mask:0xc bound_ctrl:1
	v_add_f32_dpp v39, v41, v41 row_ror:8 row_mask:0xf bank_mask:0xc bound_ctrl:1
	ds_read_b128 v[80:83], v2 offset:17664
	v_add_f32_dpp v38, v38, v38 row_half_mirror row_mask:0xf bank_mask:0x5 bound_ctrl:1
	v_add_f32_dpp v38, v39, v39 row_half_mirror row_mask:0xf bank_mask:0xa bound_ctrl:1
	ds_read_b128 v[84:87], v2 offset:17920
	ds_read_b128 v[88:91], v2 offset:18176
	v_add_f32_dpp v38, v38, v38 quad_perm:[1,0,3,2] row_mask:0xf bank_mask:0xf bound_ctrl:1
	ds_read_b128 v[92:95], v2 offset:18432
	ds_read_b64 v[96:97], v3 offset:29184
	v_add_f32_dpp v38, v38, v38 quad_perm:[2,3,0,1] row_mask:0xf bank_mask:0xf bound_ctrl:1
	ds_read_b128 v[100:103], v1 offset:30992
	v_cmp_gt_f32_e32 vcc, 0x2b8cbccc, v50
	v_fmac_f32_dpp v72, -v38, v50 row_newbcast:0 row_mask:0xf bank_mask:0xf bound_ctrl:1
	v_fmac_f32_dpp v73, -v38, v50 row_newbcast:4 row_mask:0xf bank_mask:0xf bound_ctrl:1
	v_rcp_f32_e32 v52, v50
	s_add_u32 s14, s14, 0x1000
	v_pk_mul_f32 v[44:45], v[72:73], v[76:77] op_sel:[0,1] op_sel_hi:[1,1]
	s_addc_u32 s15, s15, 0
	s_cbranch_vccnz .Lgd2_rare1_0
.Lgd2_back1_0:
	v_pk_mul_f32 v[46:47], v[44:45], v[52:53] op_sel_hi:[1,0]
	v_pk_mul_f32 v[48:49], v[44:45], v[78:79] op_sel_hi:[1,0]
	v_pk_fma_f32 v[6:7], v[56:57], v[46:47], v[6:7] op_sel_hi:[0,1,1]
	v_pk_fma_f32 v[8:9], v[58:59], v[46:47], v[8:9] op_sel_hi:[0,1,1]
	v_fmac_f32_dpp v48, v38, v50 row_newbcast:8 row_mask:0xf bank_mask:0xf bound_ctrl:1
	v_pk_fma_f32 v[10:11], v[60:61], v[46:47], v[10:11] op_sel_hi:[0,1,1]
	v_fmac_f32_dpp v49, v38, v50 row_newbcast:12 row_mask:0xf bank_mask:0xf bound_ctrl:1
	v_pk_fma_f32 v[12:13], v[62:63], v[46:47], v[12:13] op_sel_hi:[0,1,1]
	v_pk_fma_f32 v[14:15], v[64:65], v[46:47], v[14:15] op_sel_hi:[0,1,1]
	v_cvt_pk_bf16_f32 v54, v48, v49
	v_pk_fma_f32 v[16:17], v[66:67], v[46:47], v[16:17] op_sel_hi:[0,1,1]
	v_pk_fma_f32 v[18:19], v[68:69], v[46:47], v[18:19] op_sel_hi:[0,1,1]
	v_pk_fma_f32 v[20:21], v[70:71], v[46:47], v[20:21] op_sel_hi:[0,1,1]
	global_store_dword v154, v54, s[14:15] offset:-4096
	s_waitcnt lgkmcnt(5)
	v_pk_mul_f32 v[38:39], v[6:7], v[80:81] op_sel_hi:[1,0]
	v_pk_mul_f32 v[40:41], v[6:7], v[80:81] op_sel:[0,1] op_sel_hi:[1,1]
	v_pk_fma_f32 v[38:39], v[8:9], v[82:83], v[38:39] op_sel_hi:[1,0,1]
	v_pk_fma_f32 v[40:41], v[8:9], v[82:83], v[40:41] op_sel:[0,1,0] op_sel_hi:[1,1,1]
	s_waitcnt lgkmcnt(4)
	v_pk_fma_f32 v[38:39], v[10:11], v[84:85], v[38:39] op_sel_hi:[1,0,1]
	v_pk_fma_f32 v[40:41], v[10:11], v[84:85], v[40:41] op_sel:[0,1,0] op_sel_hi:[1,1,1]
	v_pk_fma_f32 v[38:39], v[12:13], v[86:87], v[38:39] op_sel_hi:[1,0,1]
	v_pk_fma_f32 v[40:41], v[12:13], v[86:87], v[40:41] op_sel:[0,1,0] op_sel_hi:[1,1,1]
	s_waitcnt lgkmcnt(3)
	v_pk_fma_f32 v[38:39], v[14:15], v[88:89], v[38:39] op_sel_hi:[1,0,1]
	v_pk_fma_f32 v[40:41], v[14:15], v[88:89], v[40:41] op_sel:[0,1,0] op_sel_hi:[1,1,1]
	v_pk_fma_f32 v[38:39], v[16:17], v[90:91], v[38:39] op_sel_hi:[1,0,1]
	v_pk_fma_f32 v[40:41], v[16:17], v[90:91], v[40:41] op_sel:[0,1,0] op_sel_hi:[1,1,1]
	s_waitcnt lgkmcnt(2)
	v_pk_fma_f32 v[38:39], v[18:19], v[92:93], v[38:39] op_sel_hi:[1,0,1]
	v_pk_fma_f32 v[40:41], v[18:19], v[92:93], v[40:41] op_sel:[0,1,0] op_sel_hi:[1,1,1]
	v_pk_fma_f32 v[38:39], v[20:21], v[94:95], v[38:39] op_sel_hi:[1,0,1]
	v_pk_fma_f32 v[40:41], v[20:21], v[94:95], v[40:41] op_sel:[0,1,0] op_sel_hi:[1,1,1]
	s_waitcnt lgkmcnt(0)
	v_mul_f32_e32 v51, v100, v50
	v_add_f32_dpp v38, v38, v38 row_ror:8 row_mask:0xf bank_mask:0x3 bound_ctrl:1
	v_add_f32_dpp v39, v39, v39 row_ror:8 row_mask:0xf bank_mask:0x3 bound_ctrl:1
	v_add_f32_dpp v38, v40, v40 row_ror:8 row_mask:0xf bank_mask:0xc bound_ctrl:1
	v_add_f32_dpp v39, v41, v41 row_ror:8 row_mask:0xf bank_mask:0xc bound_ctrl:1
	ds_read_b128 v[56:59], v2 offset:18688
	v_add_f32_dpp v38, v38, v38 row_half_mirror row_mask:0xf bank_mask:0x5 bound_ctrl:1
	v_add_f32_dpp v38, v39, v39 row_half_mirror row_mask:0xf bank_mask:0xa bound_ctrl:1
	ds_read_b128 v[60:63], v2 offset:18944
	ds_read_b128 v[64:67], v2 offset:19200
	v_add_f32_dpp v38, v38, v38 quad_perm:[1,0,3,2] row_mask:0xf bank_mask:0xf bound_ctrl:1
	ds_read_b128 v[68:71], v2 offset:19456
	ds_read_b64 v[72:73], v3 offset:29440
	v_add_f32_dpp v38, v38, v38 quad_perm:[2,3,0,1] row_mask:0xf bank_mask:0xf bound_ctrl:1
	ds_read_b128 v[76:79], v1 offset:31008
	v_cmp_gt_f32_e32 vcc, 0x2b8cbccc, v51
	v_fmac_f32_dpp v96, -v38, v51 row_newbcast:0 row_mask:0xf bank_mask:0xf bound_ctrl:1
	v_fmac_f32_dpp v97, -v38, v51 row_newbcast:4 row_mask:0xf bank_mask:0xf bound_ctrl:1
	v_rcp_f32_e32 v52, v51
	s_add_u32 s14, s14, 0x1000
	v_pk_mul_f32 v[44:45], v[96:97], v[100:101] op_sel:[0,1] op_sel_hi:[1,1]
	s_addc_u32 s15, s15, 0
	s_cbranch_vccnz .Lgd2_rare1_1
.Lgd2_back1_1:
	v_pk_mul_f32 v[46:47], v[44:45], v[52:53] op_sel_hi:[1,0]
	v_pk_mul_f32 v[48:49], v[44:45], v[102:103] op_sel_hi:[1,0]
	v_pk_fma_f32 v[6:7], v[80:81], v[46:47], v[6:7] op_sel_hi:[0,1,1]
	v_pk_fma_f32 v[8:9], v[82:83], v[46:47], v[8:9] op_sel_hi:[0,1,1]
	v_fmac_f32_dpp v48, v38, v51 row_newbcast:8 row_mask:0xf bank_mask:0xf bound_ctrl:1
	v_pk_fma_f32 v[10:11], v[84:85], v[46:47], v[10:11] op_sel_hi:[0,1,1]
	v_fmac_f32_dpp v49, v38, v51 row_newbcast:12 row_mask:0xf bank_mask:0xf bound_ctrl:1
	v_pk_fma_f32 v[12:13], v[86:87], v[46:47], v[12:13] op_sel_hi:[0,1,1]
	v_pk_fma_f32 v[14:15], v[88:89], v[46:47], v[14:15] op_sel_hi:[0,1,1]
	v_cvt_pk_bf16_f32 v54, v48, v49
	v_pk_fma_f32 v[16:17], v[90:91], v[46:47], v[16:17] op_sel_hi:[0,1,1]
	v_pk_fma_f32 v[18:19], v[92:93], v[46:47], v[18:19] op_sel_hi:[0,1,1]
	v_pk_fma_f32 v[20:21], v[94:95], v[46:47], v[20:21] op_sel_hi:[0,1,1]
	global_store_dword v154, v54, s[14:15] offset:-4096
	s_waitcnt lgkmcnt(5)
	v_pk_mul_f32 v[38:39], v[6:7], v[56:57] op_sel_hi:[1,0]
	v_pk_mul_f32 v[40:41], v[6:7], v[56:57] op_sel:[0,1] op_sel_hi:[1,1]
	v_pk_fma_f32 v[38:39], v[8:9], v[58:59], v[38:39] op_sel_hi:[1,0,1]
	v_pk_fma_f32 v[40:41], v[8:9], v[58:59], v[40:41] op_sel:[0,1,0] op_sel_hi:[1,1,1]
	s_waitcnt lgkmcnt(4)
	v_pk_fma_f32 v[38:39], v[10:11], v[60:61], v[38:39] op_sel_hi:[1,0,1]
	v_pk_fma_f32 v[40:41], v[10:11], v[60:61], v[40:41] op_sel:[0,1,0] op_sel_hi:[1,1,1]
	v_pk_fma_f32 v[38:39], v[12:13], v[62:63], v[38:39] op_sel_hi:[1,0,1]
	v_pk_fma_f32 v[40:41], v[12:13], v[62:63], v[40:41] op_sel:[0,1,0] op_sel_hi:[1,1,1]
	s_waitcnt lgkmcnt(3)
	v_pk_fma_f32 v[38:39], v[14:15], v[64:65], v[38:39] op_sel_hi:[1,0,1]
	v_pk_fma_f32 v[40:41], v[14:15], v[64:65], v[40:41] op_sel:[0,1,0] op_sel_hi:[1,1,1]
	v_pk_fma_f32 v[38:39], v[16:17], v[66:67], v[38:39] op_sel_hi:[1,0,1]
	v_pk_fma_f32 v[40:41], v[16:17], v[66:67], v[40:41] op_sel:[0,1,0] op_sel_hi:[1,1,1]
	s_waitcnt lgkmcnt(2)
	v_pk_fma_f32 v[38:39], v[18:19], v[68:69], v[38:39] op_sel_hi:[1,0,1]
	v_pk_fma_f32 v[40:41], v[18:19], v[68:69], v[40:41] op_sel:[0,1,0] op_sel_hi:[1,1,1]
	v_pk_fma_f32 v[38:39], v[20:21], v[70:71], v[38:39] op_sel_hi:[1,0,1]
	v_pk_fma_f32 v[40:41], v[20:21], v[70:71], v[40:41] op_sel:[0,1,0] op_sel_hi:[1,1,1]
	s_waitcnt lgkmcnt(0)
	v_mul_f32_e32 v50, v76, v51
	v_add_f32_dpp v38, v38, v38 row_ror:8 row_mask:0xf bank_mask:0x3 bound_ctrl:1
	v_add_f32_dpp v39, v39, v39 row_ror:8 row_mask:0xf bank_mask:0x3 bound_ctrl:1
	v_add_f32_dpp v38, v40, v40 row_ror:8 row_mask:0xf bank_mask:0xc bound_ctrl:1
	v_add_f32_dpp v39, v41, v41 row_ror:8 row_mask:0xf bank_mask:0xc bound_ctrl:1
	ds_read_b128 v[80:83], v2 offset:19712
	v_add_f32_dpp v38, v38, v38 row_half_mirror row_mask:0xf bank_mask:0x5 bound_ctrl:1
	v_add_f32_dpp v38, v39, v39 row_half_mirror row_mask:0xf bank_mask:0xa bound_ctrl:1
	ds_read_b128 v[84:87], v2 offset:19968
	ds_read_b128 v[88:91], v2 offset:20224
	v_add_f32_dpp v38, v38, v38 quad_perm:[1,0,3,2] row_mask:0xf bank_mask:0xf bound_ctrl:1
	ds_read_b128 v[92:95], v2 offset:20480
	ds_read_b64 v[96:97], v3 offset:29696
	v_add_f32_dpp v38, v38, v38 quad_perm:[2,3,0,1] row_mask:0xf bank_mask:0xf bound_ctrl:1
	ds_read_b128 v[100:103], v1 offset:31024
	v_cmp_gt_f32_e32 vcc, 0x2b8cbccc, v50
	v_fmac_f32_dpp v72, -v38, v50 row_newbcast:0 row_mask:0xf bank_mask:0xf bound_ctrl:1
	v_fmac_f32_dpp v73, -v38, v50 row_newbcast:4 row_mask:0xf bank_mask:0xf bound_ctrl:1
	v_rcp_f32_e32 v52, v50
	s_add_u32 s14, s14, 0x1000
	v_pk_mul_f32 v[44:45], v[72:73], v[76:77] op_sel:[0,1] op_sel_hi:[1,1]
	s_addc_u32 s15, s15, 0
	s_cbranch_vccnz .Lgd2_rare1_2
.Lgd2_back1_2:
	v_pk_mul_f32 v[46:47], v[44:45], v[52:53] op_sel_hi:[1,0]
	v_pk_mul_f32 v[48:49], v[44:45], v[78:79] op_sel_hi:[1,0]
	v_pk_fma_f32 v[6:7], v[56:57], v[46:47], v[6:7] op_sel_hi:[0,1,1]
	v_pk_fma_f32 v[8:9], v[58:59], v[46:47], v[8:9] op_sel_hi:[0,1,1]
	v_fmac_f32_dpp v48, v38, v50 row_newbcast:8 row_mask:0xf bank_mask:0xf bound_ctrl:1
	v_pk_fma_f32 v[10:11], v[60:61], v[46:47], v[10:11] op_sel_hi:[0,1,1]
	v_fmac_f32_dpp v49, v38, v50 row_newbcast:12 row_mask:0xf bank_mask:0xf bound_ctrl:1
	v_pk_fma_f32 v[12:13], v[62:63], v[46:47], v[12:13] op_sel_hi:[0,1,1]
	v_pk_fma_f32 v[14:15], v[64:65], v[46:47], v[14:15] op_sel_hi:[0,1,1]
	v_cvt_pk_bf16_f32 v54, v48, v49
	v_pk_fma_f32 v[16:17], v[66:67], v[46:47], v[16:17] op_sel_hi:[0,1,1]
	v_pk_fma_f32 v[18:19], v[68:69], v[46:47], v[18:19] op_sel_hi:[0,1,1]
	v_pk_fma_f32 v[20:21], v[70:71], v[46:47], v[20:21] op_sel_hi:[0,1,1]
	global_store_dword v154, v54, s[14:15] offset:-4096
	s_waitcnt lgkmcnt(5)
	v_pk_mul_f32 v[38:39], v[6:7], v[80:81] op_sel_hi:[1,0]
	v_pk_mul_f32 v[40:41], v[6:7], v[80:81] op_sel:[0,1] op_sel_hi:[1,1]
	v_pk_fma_f32 v[38:39], v[8:9], v[82:83], v[38:39] op_sel_hi:[1,0,1]
	v_pk_fma_f32 v[40:41], v[8:9], v[82:83], v[40:41] op_sel:[0,1,0] op_sel_hi:[1,1,1]
	s_waitcnt lgkmcnt(4)
	v_pk_fma_f32 v[38:39], v[10:11], v[84:85], v[38:39] op_sel_hi:[1,0,1]
	v_pk_fma_f32 v[40:41], v[10:11], v[84:85], v[40:41] op_sel:[0,1,0] op_sel_hi:[1,1,1]
	v_pk_fma_f32 v[38:39], v[12:13], v[86:87], v[38:39] op_sel_hi:[1,0,1]
	v_pk_fma_f32 v[40:41], v[12:13], v[86:87], v[40:41] op_sel:[0,1,0] op_sel_hi:[1,1,1]
	s_waitcnt lgkmcnt(3)
	v_pk_fma_f32 v[38:39], v[14:15], v[88:89], v[38:39] op_sel_hi:[1,0,1]
	v_pk_fma_f32 v[40:41], v[14:15], v[88:89], v[40:41] op_sel:[0,1,0] op_sel_hi:[1,1,1]
	v_pk_fma_f32 v[38:39], v[16:17], v[90:91], v[38:39] op_sel_hi:[1,0,1]
	v_pk_fma_f32 v[40:41], v[16:17], v[90:91], v[40:41] op_sel:[0,1,0] op_sel_hi:[1,1,1]
	s_waitcnt lgkmcnt(2)
	v_pk_fma_f32 v[38:39], v[18:19], v[92:93], v[38:39] op_sel_hi:[1,0,1]
	v_pk_fma_f32 v[40:41], v[18:19], v[92:93], v[40:41] op_sel:[0,1,0] op_sel_hi:[1,1,1]
	v_pk_fma_f32 v[38:39], v[20:21], v[94:95], v[38:39] op_sel_hi:[1,0,1]
	v_pk_fma_f32 v[40:41], v[20:21], v[94:95], v[40:41] op_sel:[0,1,0] op_sel_hi:[1,1,1]
	s_waitcnt lgkmcnt(0)
	v_mul_f32_e32 v51, v100, v50
	v_add_f32_dpp v38, v38, v38 row_ror:8 row_mask:0xf bank_mask:0x3 bound_ctrl:1
	v_add_f32_dpp v39, v39, v39 row_ror:8 row_mask:0xf bank_mask:0x3 bound_ctrl:1
	v_add_f32_dpp v38, v40, v40 row_ror:8 row_mask:0xf bank_mask:0xc bound_ctrl:1
	v_add_f32_dpp v39, v41, v41 row_ror:8 row_mask:0xf bank_mask:0xc bound_ctrl:1
	ds_read_b128 v[56:59], v2 offset:20736
	v_add_f32_dpp v38, v38, v38 row_half_mirror row_mask:0xf bank_mask:0x5 bound_ctrl:1
	v_add_f32_dpp v38, v39, v39 row_half_mirror row_mask:0xf bank_mask:0xa bound_ctrl:1
	ds_read_b128 v[60:63], v2 offset:20992
	ds_read_b128 v[64:67], v2 offset:21248
	v_add_f32_dpp v38, v38, v38 quad_perm:[1,0,3,2] row_mask:0xf bank_mask:0xf bound_ctrl:1
	ds_read_b128 v[68:71], v2 offset:21504
	ds_read_b64 v[72:73], v3 offset:29952
	v_add_f32_dpp v38, v38, v38 quad_perm:[2,3,0,1] row_mask:0xf bank_mask:0xf bound_ctrl:1
	ds_read_b128 v[76:79], v1 offset:31040
	v_cmp_gt_f32_e32 vcc, 0x2b8cbccc, v51
	v_fmac_f32_dpp v96, -v38, v51 row_newbcast:0 row_mask:0xf bank_mask:0xf bound_ctrl:1
	v_fmac_f32_dpp v97, -v38, v51 row_newbcast:4 row_mask:0xf bank_mask:0xf bound_ctrl:1
	v_rcp_f32_e32 v52, v51
	s_add_u32 s14, s14, 0x1000
	v_pk_mul_f32 v[44:45], v[96:97], v[100:101] op_sel:[0,1] op_sel_hi:[1,1]
	s_addc_u32 s15, s15, 0
	s_cbranch_vccnz .Lgd2_rare1_3
.Lgd2_back1_3:
	v_pk_mul_f32 v[46:47], v[44:45], v[52:53] op_sel_hi:[1,0]
	v_pk_mul_f32 v[48:49], v[44:45], v[102:103] op_sel_hi:[1,0]
	v_pk_fma_f32 v[6:7], v[80:81], v[46:47], v[6:7] op_sel_hi:[0,1,1]
	v_pk_fma_f32 v[8:9], v[82:83], v[46:47], v[8:9] op_sel_hi:[0,1,1]
	v_fmac_f32_dpp v48, v38, v51 row_newbcast:8 row_mask:0xf bank_mask:0xf bound_ctrl:1
	v_pk_fma_f32 v[10:11], v[84:85], v[46:47], v[10:11] op_sel_hi:[0,1,1]
	v_fmac_f32_dpp v49, v38, v51 row_newbcast:12 row_mask:0xf bank_mask:0xf bound_ctrl:1
	v_pk_fma_f32 v[12:13], v[86:87], v[46:47], v[12:13] op_sel_hi:[0,1,1]
	v_pk_fma_f32 v[14:15], v[88:89], v[46:47], v[14:15] op_sel_hi:[0,1,1]
	v_cvt_pk_bf16_f32 v54, v48, v49
	v_pk_fma_f32 v[16:17], v[90:91], v[46:47], v[16:17] op_sel_hi:[0,1,1]
	v_pk_fma_f32 v[18:19], v[92:93], v[46:47], v[18:19] op_sel_hi:[0,1,1]
	v_pk_fma_f32 v[20:21], v[94:95], v[46:47], v[20:21] op_sel_hi:[0,1,1]
	global_store_dword v154, v54, s[14:15] offset:-4096
	s_waitcnt lgkmcnt(5)
	v_pk_mul_f32 v[38:39], v[6:7], v[56:57] op_sel_hi:[1,0]
	v_pk_mul_f32 v[40:41], v[6:7], v[56:57] op_sel:[0,1] op_sel_hi:[1,1]
	v_pk_fma_f32 v[38:39], v[8:9], v[58:59], v[38:39] op_sel_hi:[1,0,1]
	v_pk_fma_f32 v[40:41], v[8:9], v[58:59], v[40:41] op_sel:[0,1,0] op_sel_hi:[1,1,1]
	s_waitcnt lgkmcnt(4)
	v_pk_fma_f32 v[38:39], v[10:11], v[60:61], v[38:39] op_sel_hi:[1,0,1]
	v_pk_fma_f32 v[40:41], v[10:11], v[60:61], v[40:41] op_sel:[0,1,0] op_sel_hi:[1,1,1]
	v_pk_fma_f32 v[38:39], v[12:13], v[62:63], v[38:39] op_sel_hi:[1,0,1]
	v_pk_fma_f32 v[40:41], v[12:13], v[62:63], v[40:41] op_sel:[0,1,0] op_sel_hi:[1,1,1]
	s_waitcnt lgkmcnt(3)
	v_pk_fma_f32 v[38:39], v[14:15], v[64:65], v[38:39] op_sel_hi:[1,0,1]
	v_pk_fma_f32 v[40:41], v[14:15], v[64:65], v[40:41] op_sel:[0,1,0] op_sel_hi:[1,1,1]
	v_pk_fma_f32 v[38:39], v[16:17], v[66:67], v[38:39] op_sel_hi:[1,0,1]
	v_pk_fma_f32 v[40:41], v[16:17], v[66:67], v[40:41] op_sel:[0,1,0] op_sel_hi:[1,1,1]
	s_waitcnt lgkmcnt(2)
	v_pk_fma_f32 v[38:39], v[18:19], v[68:69], v[38:39] op_sel_hi:[1,0,1]
	v_pk_fma_f32 v[40:41], v[18:19], v[68:69], v[40:41] op_sel:[0,1,0] op_sel_hi:[1,1,1]
	v_pk_fma_f32 v[38:39], v[20:21], v[70:71], v[38:39] op_sel_hi:[1,0,1]
	v_pk_fma_f32 v[40:41], v[20:21], v[70:71], v[40:41] op_sel:[0,1,0] op_sel_hi:[1,1,1]
	s_waitcnt lgkmcnt(0)
	v_mul_f32_e32 v50, v76, v51
	v_add_f32_dpp v38, v38, v38 row_ror:8 row_mask:0xf bank_mask:0x3 bound_ctrl:1
	v_add_f32_dpp v39, v39, v39 row_ror:8 row_mask:0xf bank_mask:0x3 bound_ctrl:1
	v_add_f32_dpp v38, v40, v40 row_ror:8 row_mask:0xf bank_mask:0xc bound_ctrl:1
	v_add_f32_dpp v39, v41, v41 row_ror:8 row_mask:0xf bank_mask:0xc bound_ctrl:1
	ds_read_b128 v[80:83], v2 offset:21760
	v_add_f32_dpp v38, v38, v38 row_half_mirror row_mask:0xf bank_mask:0x5 bound_ctrl:1
	v_add_f32_dpp v38, v39, v39 row_half_mirror row_mask:0xf bank_mask:0xa bound_ctrl:1
	ds_read_b128 v[84:87], v2 offset:22016
	ds_read_b128 v[88:91], v2 offset:22272
	v_add_f32_dpp v38, v38, v38 quad_perm:[1,0,3,2] row_mask:0xf bank_mask:0xf bound_ctrl:1
	ds_read_b128 v[92:95], v2 offset:22528
	ds_read_b64 v[96:97], v3 offset:30208
	v_add_f32_dpp v38, v38, v38 quad_perm:[2,3,0,1] row_mask:0xf bank_mask:0xf bound_ctrl:1
	ds_read_b128 v[100:103], v1 offset:31056
	v_cmp_gt_f32_e32 vcc, 0x2b8cbccc, v50
	v_fmac_f32_dpp v72, -v38, v50 row_newbcast:0 row_mask:0xf bank_mask:0xf bound_ctrl:1
	v_fmac_f32_dpp v73, -v38, v50 row_newbcast:4 row_mask:0xf bank_mask:0xf bound_ctrl:1
	v_rcp_f32_e32 v52, v50
	s_add_u32 s14, s14, 0x1000
	v_pk_mul_f32 v[44:45], v[72:73], v[76:77] op_sel:[0,1] op_sel_hi:[1,1]
	s_addc_u32 s15, s15, 0
	s_cbranch_vccnz .Lgd2_rare1_4
.Lgd2_back1_4:
	v_pk_mul_f32 v[46:47], v[44:45], v[52:53] op_sel_hi:[1,0]
	v_pk_mul_f32 v[48:49], v[44:45], v[78:79] op_sel_hi:[1,0]
	v_pk_fma_f32 v[6:7], v[56:57], v[46:47], v[6:7] op_sel_hi:[0,1,1]
	v_pk_fma_f32 v[8:9], v[58:59], v[46:47], v[8:9] op_sel_hi:[0,1,1]
	v_fmac_f32_dpp v48, v38, v50 row_newbcast:8 row_mask:0xf bank_mask:0xf bound_ctrl:1
	v_pk_fma_f32 v[10:11], v[60:61], v[46:47], v[10:11] op_sel_hi:[0,1,1]
	v_fmac_f32_dpp v49, v38, v50 row_newbcast:12 row_mask:0xf bank_mask:0xf bound_ctrl:1
	v_pk_fma_f32 v[12:13], v[62:63], v[46:47], v[12:13] op_sel_hi:[0,1,1]
	v_pk_fma_f32 v[14:15], v[64:65], v[46:47], v[14:15] op_sel_hi:[0,1,1]
	v_cvt_pk_bf16_f32 v54, v48, v49
	v_pk_fma_f32 v[16:17], v[66:67], v[46:47], v[16:17] op_sel_hi:[0,1,1]
	v_pk_fma_f32 v[18:19], v[68:69], v[46:47], v[18:19] op_sel_hi:[0,1,1]
	v_pk_fma_f32 v[20:21], v[70:71], v[46:47], v[20:21] op_sel_hi:[0,1,1]
	global_store_dword v154, v54, s[14:15] offset:-4096
	s_waitcnt lgkmcnt(5)
	v_pk_mul_f32 v[38:39], v[6:7], v[80:81] op_sel_hi:[1,0]
	v_pk_mul_f32 v[40:41], v[6:7], v[80:81] op_sel:[0,1] op_sel_hi:[1,1]
	v_pk_fma_f32 v[38:39], v[8:9], v[82:83], v[38:39] op_sel_hi:[1,0,1]
	v_pk_fma_f32 v[40:41], v[8:9], v[82:83], v[40:41] op_sel:[0,1,0] op_sel_hi:[1,1,1]
	s_waitcnt lgkmcnt(4)
	v_pk_fma_f32 v[38:39], v[10:11], v[84:85], v[38:39] op_sel_hi:[1,0,1]
	v_pk_fma_f32 v[40:41], v[10:11], v[84:85], v[40:41] op_sel:[0,1,0] op_sel_hi:[1,1,1]
	v_pk_fma_f32 v[38:39], v[12:13], v[86:87], v[38:39] op_sel_hi:[1,0,1]
	v_pk_fma_f32 v[40:41], v[12:13], v[86:87], v[40:41] op_sel:[0,1,0] op_sel_hi:[1,1,1]
	s_waitcnt lgkmcnt(3)
	v_pk_fma_f32 v[38:39], v[14:15], v[88:89], v[38:39] op_sel_hi:[1,0,1]
	v_pk_fma_f32 v[40:41], v[14:15], v[88:89], v[40:41] op_sel:[0,1,0] op_sel_hi:[1,1,1]
	v_pk_fma_f32 v[38:39], v[16:17], v[90:91], v[38:39] op_sel_hi:[1,0,1]
	v_pk_fma_f32 v[40:41], v[16:17], v[90:91], v[40:41] op_sel:[0,1,0] op_sel_hi:[1,1,1]
	s_waitcnt lgkmcnt(2)
	v_pk_fma_f32 v[38:39], v[18:19], v[92:93], v[38:39] op_sel_hi:[1,0,1]
	v_pk_fma_f32 v[40:41], v[18:19], v[92:93], v[40:41] op_sel:[0,1,0] op_sel_hi:[1,1,1]
	v_pk_fma_f32 v[38:39], v[20:21], v[94:95], v[38:39] op_sel_hi:[1,0,1]
	v_pk_fma_f32 v[40:41], v[20:21], v[94:95], v[40:41] op_sel:[0,1,0] op_sel_hi:[1,1,1]
	s_waitcnt lgkmcnt(0)
	v_mul_f32_e32 v51, v100, v50
	v_add_f32_dpp v38, v38, v38 row_ror:8 row_mask:0xf bank_mask:0x3 bound_ctrl:1
	v_add_f32_dpp v39, v39, v39 row_ror:8 row_mask:0xf bank_mask:0x3 bound_ctrl:1
	v_add_f32_dpp v38, v40, v40 row_ror:8 row_mask:0xf bank_mask:0xc bound_ctrl:1
	v_add_f32_dpp v39, v41, v41 row_ror:8 row_mask:0xf bank_mask:0xc bound_ctrl:1
	ds_read_b128 v[56:59], v2 offset:22784
	v_add_f32_dpp v38, v38, v38 row_half_mirror row_mask:0xf bank_mask:0x5 bound_ctrl:1
	v_add_f32_dpp v38, v39, v39 row_half_mirror row_mask:0xf bank_mask:0xa bound_ctrl:1
	ds_read_b128 v[60:63], v2 offset:23040
	ds_read_b128 v[64:67], v2 offset:23296
	v_add_f32_dpp v38, v38, v38 quad_perm:[1,0,3,2] row_mask:0xf bank_mask:0xf bound_ctrl:1
	ds_read_b128 v[68:71], v2 offset:23552
	ds_read_b64 v[72:73], v3 offset:30464
	v_add_f32_dpp v38, v38, v38 quad_perm:[2,3,0,1] row_mask:0xf bank_mask:0xf bound_ctrl:1
	ds_read_b128 v[76:79], v1 offset:31072
	v_cmp_gt_f32_e32 vcc, 0x2b8cbccc, v51
	v_fmac_f32_dpp v96, -v38, v51 row_newbcast:0 row_mask:0xf bank_mask:0xf bound_ctrl:1
	v_fmac_f32_dpp v97, -v38, v51 row_newbcast:4 row_mask:0xf bank_mask:0xf bound_ctrl:1
	v_rcp_f32_e32 v52, v51
	s_add_u32 s14, s14, 0x1000
	v_pk_mul_f32 v[44:45], v[96:97], v[100:101] op_sel:[0,1] op_sel_hi:[1,1]
	s_addc_u32 s15, s15, 0
	s_cbranch_vccnz .Lgd2_rare1_5
.Lgd2_back1_5:
	v_pk_mul_f32 v[46:47], v[44:45], v[52:53] op_sel_hi:[1,0]
	v_pk_mul_f32 v[48:49], v[44:45], v[102:103] op_sel_hi:[1,0]
	v_pk_fma_f32 v[6:7], v[80:81], v[46:47], v[6:7] op_sel_hi:[0,1,1]
	v_pk_fma_f32 v[8:9], v[82:83], v[46:47], v[8:9] op_sel_hi:[0,1,1]
	v_fmac_f32_dpp v48, v38, v51 row_newbcast:8 row_mask:0xf bank_mask:0xf bound_ctrl:1
	v_pk_fma_f32 v[10:11], v[84:85], v[46:47], v[10:11] op_sel_hi:[0,1,1]
	v_fmac_f32_dpp v49, v38, v51 row_newbcast:12 row_mask:0xf bank_mask:0xf bound_ctrl:1
	v_pk_fma_f32 v[12:13], v[86:87], v[46:47], v[12:13] op_sel_hi:[0,1,1]
	v_pk_fma_f32 v[14:15], v[88:89], v[46:47], v[14:15] op_sel_hi:[0,1,1]
	v_cvt_pk_bf16_f32 v54, v48, v49
	v_pk_fma_f32 v[16:17], v[90:91], v[46:47], v[16:17] op_sel_hi:[0,1,1]
	v_pk_fma_f32 v[18:19], v[92:93], v[46:47], v[18:19] op_sel_hi:[0,1,1]
	v_pk_fma_f32 v[20:21], v[94:95], v[46:47], v[20:21] op_sel_hi:[0,1,1]
	global_store_dword v154, v54, s[14:15] offset:-4096
	s_waitcnt lgkmcnt(5)
	v_pk_mul_f32 v[38:39], v[6:7], v[56:57] op_sel_hi:[1,0]
	v_pk_mul_f32 v[40:41], v[6:7], v[56:57] op_sel:[0,1] op_sel_hi:[1,1]
	v_pk_fma_f32 v[38:39], v[8:9], v[58:59], v[38:39] op_sel_hi:[1,0,1]
	v_pk_fma_f32 v[40:41], v[8:9], v[58:59], v[40:41] op_sel:[0,1,0] op_sel_hi:[1,1,1]
	s_waitcnt lgkmcnt(4)
	v_pk_fma_f32 v[38:39], v[10:11], v[60:61], v[38:39] op_sel_hi:[1,0,1]
	v_pk_fma_f32 v[40:41], v[10:11], v[60:61], v[40:41] op_sel:[0,1,0] op_sel_hi:[1,1,1]
	v_pk_fma_f32 v[38:39], v[12:13], v[62:63], v[38:39] op_sel_hi:[1,0,1]
	v_pk_fma_f32 v[40:41], v[12:13], v[62:63], v[40:41] op_sel:[0,1,0] op_sel_hi:[1,1,1]
	s_waitcnt lgkmcnt(3)
	v_pk_fma_f32 v[38:39], v[14:15], v[64:65], v[38:39] op_sel_hi:[1,0,1]
	v_pk_fma_f32 v[40:41], v[14:15], v[64:65], v[40:41] op_sel:[0,1,0] op_sel_hi:[1,1,1]
	v_pk_fma_f32 v[38:39], v[16:17], v[66:67], v[38:39] op_sel_hi:[1,0,1]
	v_pk_fma_f32 v[40:41], v[16:17], v[66:67], v[40:41] op_sel:[0,1,0] op_sel_hi:[1,1,1]
	s_waitcnt lgkmcnt(2)
	v_pk_fma_f32 v[38:39], v[18:19], v[68:69], v[38:39] op_sel_hi:[1,0,1]
	v_pk_fma_f32 v[40:41], v[18:19], v[68:69], v[40:41] op_sel:[0,1,0] op_sel_hi:[1,1,1]
	v_pk_fma_f32 v[38:39], v[20:21], v[70:71], v[38:39] op_sel_hi:[1,0,1]
	v_pk_fma_f32 v[40:41], v[20:21], v[70:71], v[40:41] op_sel:[0,1,0] op_sel_hi:[1,1,1]
	s_waitcnt lgkmcnt(0)
	v_mul_f32_e32 v50, v76, v51
	v_add_f32_dpp v38, v38, v38 row_ror:8 row_mask:0xf bank_mask:0x3 bound_ctrl:1
	v_add_f32_dpp v39, v39, v39 row_ror:8 row_mask:0xf bank_mask:0x3 bound_ctrl:1
	v_add_f32_dpp v38, v40, v40 row_ror:8 row_mask:0xf bank_mask:0xc bound_ctrl:1
	v_add_f32_dpp v39, v41, v41 row_ror:8 row_mask:0xf bank_mask:0xc bound_ctrl:1
	ds_read_b128 v[80:83], v2 offset:23808
	v_add_f32_dpp v38, v38, v38 row_half_mirror row_mask:0xf bank_mask:0x5 bound_ctrl:1
	v_add_f32_dpp v38, v39, v39 row_half_mirror row_mask:0xf bank_mask:0xa bound_ctrl:1
	ds_read_b128 v[84:87], v2 offset:24064
	ds_read_b128 v[88:91], v2 offset:24320
	v_add_f32_dpp v38, v38, v38 quad_perm:[1,0,3,2] row_mask:0xf bank_mask:0xf bound_ctrl:1
	ds_read_b128 v[92:95], v2 offset:24576
	ds_read_b64 v[96:97], v3 offset:30720
	v_add_f32_dpp v38, v38, v38 quad_perm:[2,3,0,1] row_mask:0xf bank_mask:0xf bound_ctrl:1
	ds_read_b128 v[100:103], v1 offset:31088
	v_cmp_gt_f32_e32 vcc, 0x2b8cbccc, v50
	v_fmac_f32_dpp v72, -v38, v50 row_newbcast:0 row_mask:0xf bank_mask:0xf bound_ctrl:1
	v_fmac_f32_dpp v73, -v38, v50 row_newbcast:4 row_mask:0xf bank_mask:0xf bound_ctrl:1
	v_rcp_f32_e32 v52, v50
	s_add_u32 s14, s14, 0x1000
	v_pk_mul_f32 v[44:45], v[72:73], v[76:77] op_sel:[0,1] op_sel_hi:[1,1]
	s_addc_u32 s15, s15, 0
	s_cbranch_vccnz .Lgd2_rare1_6
.Lgd2_back1_6:
	v_pk_mul_f32 v[46:47], v[44:45], v[52:53] op_sel_hi:[1,0]
	v_pk_mul_f32 v[48:49], v[44:45], v[78:79] op_sel_hi:[1,0]
	v_pk_fma_f32 v[6:7], v[56:57], v[46:47], v[6:7] op_sel_hi:[0,1,1]
	v_pk_fma_f32 v[8:9], v[58:59], v[46:47], v[8:9] op_sel_hi:[0,1,1]
	v_fmac_f32_dpp v48, v38, v50 row_newbcast:8 row_mask:0xf bank_mask:0xf bound_ctrl:1
	v_pk_fma_f32 v[10:11], v[60:61], v[46:47], v[10:11] op_sel_hi:[0,1,1]
	v_fmac_f32_dpp v49, v38, v50 row_newbcast:12 row_mask:0xf bank_mask:0xf bound_ctrl:1
	v_pk_fma_f32 v[12:13], v[62:63], v[46:47], v[12:13] op_sel_hi:[0,1,1]
	v_pk_fma_f32 v[14:15], v[64:65], v[46:47], v[14:15] op_sel_hi:[0,1,1]
	v_cvt_pk_bf16_f32 v54, v48, v49
	v_pk_fma_f32 v[16:17], v[66:67], v[46:47], v[16:17] op_sel_hi:[0,1,1]
	v_pk_fma_f32 v[18:19], v[68:69], v[46:47], v[18:19] op_sel_hi:[0,1,1]
	v_pk_fma_f32 v[20:21], v[70:71], v[46:47], v[20:21] op_sel_hi:[0,1,1]
	global_store_dword v154, v54, s[14:15] offset:-4096
	s_waitcnt lgkmcnt(5)
	v_pk_mul_f32 v[38:39], v[6:7], v[80:81] op_sel_hi:[1,0]
	v_pk_mul_f32 v[40:41], v[6:7], v[80:81] op_sel:[0,1] op_sel_hi:[1,1]
	v_pk_fma_f32 v[38:39], v[8:9], v[82:83], v[38:39] op_sel_hi:[1,0,1]
	v_pk_fma_f32 v[40:41], v[8:9], v[82:83], v[40:41] op_sel:[0,1,0] op_sel_hi:[1,1,1]
	s_waitcnt lgkmcnt(4)
	v_pk_fma_f32 v[38:39], v[10:11], v[84:85], v[38:39] op_sel_hi:[1,0,1]
	v_pk_fma_f32 v[40:41], v[10:11], v[84:85], v[40:41] op_sel:[0,1,0] op_sel_hi:[1,1,1]
	v_pk_fma_f32 v[38:39], v[12:13], v[86:87], v[38:39] op_sel_hi:[1,0,1]
	v_pk_fma_f32 v[40:41], v[12:13], v[86:87], v[40:41] op_sel:[0,1,0] op_sel_hi:[1,1,1]
	s_waitcnt lgkmcnt(3)
	v_pk_fma_f32 v[38:39], v[14:15], v[88:89], v[38:39] op_sel_hi:[1,0,1]
	v_pk_fma_f32 v[40:41], v[14:15], v[88:89], v[40:41] op_sel:[0,1,0] op_sel_hi:[1,1,1]
	v_pk_fma_f32 v[38:39], v[16:17], v[90:91], v[38:39] op_sel_hi:[1,0,1]
	v_pk_fma_f32 v[40:41], v[16:17], v[90:91], v[40:41] op_sel:[0,1,0] op_sel_hi:[1,1,1]
	s_waitcnt lgkmcnt(2)
	v_pk_fma_f32 v[38:39], v[18:19], v[92:93], v[38:39] op_sel_hi:[1,0,1]
	v_pk_fma_f32 v[40:41], v[18:19], v[92:93], v[40:41] op_sel:[0,1,0] op_sel_hi:[1,1,1]
	v_pk_fma_f32 v[38:39], v[20:21], v[94:95], v[38:39] op_sel_hi:[1,0,1]
	v_pk_fma_f32 v[40:41], v[20:21], v[94:95], v[40:41] op_sel:[0,1,0] op_sel_hi:[1,1,1]
	s_waitcnt lgkmcnt(0)
	v_mul_f32_e32 v51, v100, v50
	v_add_f32_dpp v38, v38, v38 row_ror:8 row_mask:0xf bank_mask:0x3 bound_ctrl:1
	v_add_f32_dpp v39, v39, v39 row_ror:8 row_mask:0xf bank_mask:0x3 bound_ctrl:1
	v_add_f32_dpp v38, v40, v40 row_ror:8 row_mask:0xf bank_mask:0xc bound_ctrl:1
	v_add_f32_dpp v39, v41, v41 row_ror:8 row_mask:0xf bank_mask:0xc bound_ctrl:1
	ds_read_b128 v[56:59], v2 offset:33024
	v_add_f32_dpp v38, v38, v38 row_half_mirror row_mask:0xf bank_mask:0x5 bound_ctrl:1
	v_add_f32_dpp v38, v39, v39 row_half_mirror row_mask:0xf bank_mask:0xa bound_ctrl:1
	ds_read_b128 v[60:63], v2 offset:33280
	ds_read_b128 v[64:67], v2 offset:33536
	v_add_f32_dpp v38, v38, v38 quad_perm:[1,0,3,2] row_mask:0xf bank_mask:0xf bound_ctrl:1
	ds_read_b128 v[68:71], v2 offset:33792
	ds_read_b64 v[72:73], v3 offset:45312
	v_add_f32_dpp v38, v38, v38 quad_perm:[2,3,0,1] row_mask:0xf bank_mask:0xf bound_ctrl:1
	ds_read_b128 v[76:79], v1 offset:47360
	v_cmp_gt_f32_e32 vcc, 0x2b8cbccc, v51
	v_fmac_f32_dpp v96, -v38, v51 row_newbcast:0 row_mask:0xf bank_mask:0xf bound_ctrl:1
	v_fmac_f32_dpp v97, -v38, v51 row_newbcast:4 row_mask:0xf bank_mask:0xf bound_ctrl:1
	v_rcp_f32_e32 v52, v51
	s_add_u32 s14, s14, 0x1000
	v_pk_mul_f32 v[44:45], v[96:97], v[100:101] op_sel:[0,1] op_sel_hi:[1,1]
	s_addc_u32 s15, s15, 0
	s_cbranch_vccnz .Lgd2_rare1_7
.Lgd2_back1_7:
	v_pk_mul_f32 v[46:47], v[44:45], v[52:53] op_sel_hi:[1,0]
	v_pk_mul_f32 v[48:49], v[44:45], v[102:103] op_sel_hi:[1,0]
	v_pk_fma_f32 v[6:7], v[80:81], v[46:47], v[6:7] op_sel_hi:[0,1,1]
	v_pk_fma_f32 v[8:9], v[82:83], v[46:47], v[8:9] op_sel_hi:[0,1,1]
	v_fmac_f32_dpp v48, v38, v51 row_newbcast:8 row_mask:0xf bank_mask:0xf bound_ctrl:1
	v_pk_fma_f32 v[10:11], v[84:85], v[46:47], v[10:11] op_sel_hi:[0,1,1]
	v_fmac_f32_dpp v49, v38, v51 row_newbcast:12 row_mask:0xf bank_mask:0xf bound_ctrl:1
	v_pk_fma_f32 v[12:13], v[86:87], v[46:47], v[12:13] op_sel_hi:[0,1,1]
	v_pk_fma_f32 v[14:15], v[88:89], v[46:47], v[14:15] op_sel_hi:[0,1,1]
	v_cvt_pk_bf16_f32 v54, v48, v49
	v_pk_fma_f32 v[16:17], v[90:91], v[46:47], v[16:17] op_sel_hi:[0,1,1]
	v_pk_fma_f32 v[18:19], v[92:93], v[46:47], v[18:19] op_sel_hi:[0,1,1]
	v_pk_fma_f32 v[20:21], v[94:95], v[46:47], v[20:21] op_sel_hi:[0,1,1]
	global_store_dword v154, v54, s[14:15] offset:-4096
	s_waitcnt vmcnt(8)
	v_lshlrev_b32_e32 v116, 16, v108
	v_lshlrev_b32_e32 v117, 16, v109
	v_and_b32_e32 v118, s17, v108
	v_and_b32_e32 v119, s17, v109
	v_lshlrev_b32_e32 v120, 16, v110
	v_and_b32_e32 v121, s17, v110
	v_lshlrev_b32_e32 v122, 16, v111
	v_and_b32_e32 v123, s17, v111
	v_lshlrev_b32_e32 v124, 16, v112
	v_and_b32_e32 v125, s17, v112
	ds_write_b128 v32, v[116:119] offset:256
	ds_write_b64 v33, v[120:121] offset:256
	ds_write_b64 v34, v[122:123] offset:256
	ds_write_b64 v34, v[124:125] offset:384
	ds_write_b32 v35, v113 offset:256
	s_add_i32 s16, s16, 8
	s_waitcnt lgkmcnt(0)
	s_barrier
	s_cmpk_lt_u32 s16, 0x800
	s_cbranch_scc0 .Lgd2_done
	global_load_dword v108, v36, s[8:9]
	global_load_dword v109, v36, s[8:9] offset:-2048
	global_load_dword v111, v104, s[8:9] offset:2048
	global_load_dword v110, v37, s[10:11]
	global_load_dword v112, v105, s[10:11]
	global_load_dword v113, v106, s[12:13]
	s_add_u32 s8, s8, 0xc000
	s_addc_u32 s9, s9, 0
	s_add_u32 s10, s10, 0x20000
	s_addc_u32 s11, s11, 0
	s_add_u32 s12, s12, 0x400
	s_addc_u32 s13, s13, 0
	s_waitcnt lgkmcnt(5)
	v_pk_mul_f32 v[38:39], v[6:7], v[56:57] op_sel_hi:[1,0]
	v_pk_mul_f32 v[40:41], v[6:7], v[56:57] op_sel:[0,1] op_sel_hi:[1,1]
	v_pk_fma_f32 v[38:39], v[8:9], v[58:59], v[38:39] op_sel_hi:[1,0,1]
	v_pk_fma_f32 v[40:41], v[8:9], v[58:59], v[40:41] op_sel:[0,1,0] op_sel_hi:[1,1,1]
	s_waitcnt lgkmcnt(4)
	v_pk_fma_f32 v[38:39], v[10:11], v[60:61], v[38:39] op_sel_hi:[1,0,1]
	v_pk_fma_f32 v[40:41], v[10:11], v[60:61], v[40:41] op_sel:[0,1,0] op_sel_hi:[1,1,1]
	v_pk_fma_f32 v[38:39], v[12:13], v[62:63], v[38:39] op_sel_hi:[1,0,1]
	v_pk_fma_f32 v[40:41], v[12:13], v[62:63], v[40:41] op_sel:[0,1,0] op_sel_hi:[1,1,1]
	s_waitcnt lgkmcnt(3)
	v_pk_fma_f32 v[38:39], v[14:15], v[64:65], v[38:39] op_sel_hi:[1,0,1]
	v_pk_fma_f32 v[40:41], v[14:15], v[64:65], v[40:41] op_sel:[0,1,0] op_sel_hi:[1,1,1]
	v_pk_fma_f32 v[38:39], v[16:17], v[66:67], v[38:39] op_sel_hi:[1,0,1]
	v_pk_fma_f32 v[40:41], v[16:17], v[66:67], v[40:41] op_sel:[0,1,0] op_sel_hi:[1,1,1]
	s_waitcnt lgkmcnt(2)
	v_pk_fma_f32 v[38:39], v[18:19], v[68:69], v[38:39] op_sel_hi:[1,0,1]
	v_pk_fma_f32 v[40:41], v[18:19], v[68:69], v[40:41] op_sel:[0,1,0] op_sel_hi:[1,1,1]
	v_pk_fma_f32 v[38:39], v[20:21], v[70:71], v[38:39] op_sel_hi:[1,0,1]
	v_pk_fma_f32 v[40:41], v[20:21], v[70:71], v[40:41] op_sel:[0,1,0] op_sel_hi:[1,1,1]
	s_waitcnt lgkmcnt(0)
	v_mul_f32_e32 v50, v76, v51
	v_add_f32_dpp v38, v38, v38 row_ror:8 row_mask:0xf bank_mask:0x3 bound_ctrl:1
	v_add_f32_dpp v39, v39, v39 row_ror:8 row_mask:0xf bank_mask:0x3 bound_ctrl:1
	v_add_f32_dpp v38, v40, v40 row_ror:8 row_mask:0xf bank_mask:0xc bound_ctrl:1
	v_add_f32_dpp v39, v41, v41 row_ror:8 row_mask:0xf bank_mask:0xc bound_ctrl:1
	ds_read_b128 v[80:83], v2 offset:34048
	v_add_f32_dpp v38, v38, v38 row_half_mirror row_mask:0xf bank_mask:0x5 bound_ctrl:1
	v_add_f32_dpp v38, v39, v39 row_half_mirror row_mask:0xf bank_mask:0xa bound_ctrl:1
	ds_read_b128 v[84:87], v2 offset:34304
	ds_read_b128 v[88:91], v2 offset:34560
	v_add_f32_dpp v38, v38, v38 quad_perm:[1,0,3,2] row_mask:0xf bank_mask:0xf bound_ctrl:1
	ds_read_b128 v[92:95], v2 offset:34816
	ds_read_b64 v[96:97], v3 offset:45568
	v_add_f32_dpp v38, v38, v38 quad_perm:[2,3,0,1] row_mask:0xf bank_mask:0xf bound_ctrl:1
	ds_read_b128 v[100:103], v1 offset:47376
	v_cmp_gt_f32_e32 vcc, 0x2b8cbccc, v50
	v_fmac_f32_dpp v72, -v38, v50 row_newbcast:0 row_mask:0xf bank_mask:0xf bound_ctrl:1
	v_fmac_f32_dpp v73, -v38, v50 row_newbcast:4 row_mask:0xf bank_mask:0xf bound_ctrl:1
	v_rcp_f32_e32 v52, v50
	s_add_u32 s14, s14, 0x1000
	v_pk_mul_f32 v[44:45], v[72:73], v[76:77] op_sel:[0,1] op_sel_hi:[1,1]
	s_addc_u32 s15, s15, 0
	s_cbranch_vccnz .Lgd2_rare2_0
.Lgd2_back2_0:
	v_pk_mul_f32 v[46:47], v[44:45], v[52:53] op_sel_hi:[1,0]
	v_pk_mul_f32 v[48:49], v[44:45], v[78:79] op_sel_hi:[1,0]
	v_pk_fma_f32 v[6:7], v[56:57], v[46:47], v[6:7] op_sel_hi:[0,1,1]
	v_pk_fma_f32 v[8:9], v[58:59], v[46:47], v[8:9] op_sel_hi:[0,1,1]
	v_fmac_f32_dpp v48, v38, v50 row_newbcast:8 row_mask:0xf bank_mask:0xf bound_ctrl:1
	v_pk_fma_f32 v[10:11], v[60:61], v[46:47], v[10:11] op_sel_hi:[0,1,1]
	v_fmac_f32_dpp v49, v38, v50 row_newbcast:12 row_mask:0xf bank_mask:0xf bound_ctrl:1
	v_pk_fma_f32 v[12:13], v[62:63], v[46:47], v[12:13] op_sel_hi:[0,1,1]
	v_pk_fma_f32 v[14:15], v[64:65], v[46:47], v[14:15] op_sel_hi:[0,1,1]
	v_cvt_pk_bf16_f32 v54, v48, v49
	v_pk_fma_f32 v[16:17], v[66:67], v[46:47], v[16:17] op_sel_hi:[0,1,1]
	v_pk_fma_f32 v[18:19], v[68:69], v[46:47], v[18:19] op_sel_hi:[0,1,1]
	v_pk_fma_f32 v[20:21], v[70:71], v[46:47], v[20:21] op_sel_hi:[0,1,1]
	global_store_dword v154, v54, s[14:15] offset:-4096
	s_waitcnt lgkmcnt(5)
	v_pk_mul_f32 v[38:39], v[6:7], v[80:81] op_sel_hi:[1,0]
	v_pk_mul_f32 v[40:41], v[6:7], v[80:81] op_sel:[0,1] op_sel_hi:[1,1]
	v_pk_fma_f32 v[38:39], v[8:9], v[82:83], v[38:39] op_sel_hi:[1,0,1]
	v_pk_fma_f32 v[40:41], v[8:9], v[82:83], v[40:41] op_sel:[0,1,0] op_sel_hi:[1,1,1]
	s_waitcnt lgkmcnt(4)
	v_pk_fma_f32 v[38:39], v[10:11], v[84:85], v[38:39] op_sel_hi:[1,0,1]
	v_pk_fma_f32 v[40:41], v[10:11], v[84:85], v[40:41] op_sel:[0,1,0] op_sel_hi:[1,1,1]
	v_pk_fma_f32 v[38:39], v[12:13], v[86:87], v[38:39] op_sel_hi:[1,0,1]
	v_pk_fma_f32 v[40:41], v[12:13], v[86:87], v[40:41] op_sel:[0,1,0] op_sel_hi:[1,1,1]
	s_waitcnt lgkmcnt(3)
	v_pk_fma_f32 v[38:39], v[14:15], v[88:89], v[38:39] op_sel_hi:[1,0,1]
	v_pk_fma_f32 v[40:41], v[14:15], v[88:89], v[40:41] op_sel:[0,1,0] op_sel_hi:[1,1,1]
	v_pk_fma_f32 v[38:39], v[16:17], v[90:91], v[38:39] op_sel_hi:[1,0,1]
	v_pk_fma_f32 v[40:41], v[16:17], v[90:91], v[40:41] op_sel:[0,1,0] op_sel_hi:[1,1,1]
	s_waitcnt lgkmcnt(2)
	v_pk_fma_f32 v[38:39], v[18:19], v[92:93], v[38:39] op_sel_hi:[1,0,1]
	v_pk_fma_f32 v[40:41], v[18:19], v[92:93], v[40:41] op_sel:[0,1,0] op_sel_hi:[1,1,1]
	v_pk_fma_f32 v[38:39], v[20:21], v[94:95], v[38:39] op_sel_hi:[1,0,1]
	v_pk_fma_f32 v[40:41], v[20:21], v[94:95], v[40:41] op_sel:[0,1,0] op_sel_hi:[1,1,1]
	s_waitcnt lgkmcnt(0)
	v_mul_f32_e32 v51, v100, v50
	v_add_f32_dpp v38, v38, v38 row_ror:8 row_mask:0xf bank_mask:0x3 bound_ctrl:1
	v_add_f32_dpp v39, v39, v39 row_ror:8 row_mask:0xf bank_mask:0x3 bound_ctrl:1
	v_add_f32_dpp v38, v40, v40 row_ror:8 row_mask:0xf bank_mask:0xc bound_ctrl:1
	v_add_f32_dpp v39, v41, v41 row_ror:8 row_mask:0xf bank_mask:0xc bound_ctrl:1
	ds_read_b128 v[56:59], v2 offset:35072
	v_add_f32_dpp v38, v38, v38 row_half_mirror row_mask:0xf bank_mask:0x5 bound_ctrl:1
	v_add_f32_dpp v38, v39, v39 row_half_mirror row_mask:0xf bank_mask:0xa bound_ctrl:1
	ds_read_b128 v[60:63], v2 offset:35328
	ds_read_b128 v[64:67], v2 offset:35584
	v_add_f32_dpp v38, v38, v38 quad_perm:[1,0,3,2] row_mask:0xf bank_mask:0xf bound_ctrl:1
	ds_read_b128 v[68:71], v2 offset:35840
	ds_read_b64 v[72:73], v3 offset:45824
	v_add_f32_dpp v38, v38, v38 quad_perm:[2,3,0,1] row_mask:0xf bank_mask:0xf bound_ctrl:1
	ds_read_b128 v[76:79], v1 offset:47392
	v_cmp_gt_f32_e32 vcc, 0x2b8cbccc, v51
	v_fmac_f32_dpp v96, -v38, v51 row_newbcast:0 row_mask:0xf bank_mask:0xf bound_ctrl:1
	v_fmac_f32_dpp v97, -v38, v51 row_newbcast:4 row_mask:0xf bank_mask:0xf bound_ctrl:1
	v_rcp_f32_e32 v52, v51
	s_add_u32 s14, s14, 0x1000
	v_pk_mul_f32 v[44:45], v[96:97], v[100:101] op_sel:[0,1] op_sel_hi:[1,1]
	s_addc_u32 s15, s15, 0
	s_cbranch_vccnz .Lgd2_rare2_1
.Lgd2_back2_1:
	v_pk_mul_f32 v[46:47], v[44:45], v[52:53] op_sel_hi:[1,0]
	v_pk_mul_f32 v[48:49], v[44:45], v[102:103] op_sel_hi:[1,0]
	v_pk_fma_f32 v[6:7], v[80:81], v[46:47], v[6:7] op_sel_hi:[0,1,1]
	v_pk_fma_f32 v[8:9], v[82:83], v[46:47], v[8:9] op_sel_hi:[0,1,1]
	v_fmac_f32_dpp v48, v38, v51 row_newbcast:8 row_mask:0xf bank_mask:0xf bound_ctrl:1
	v_pk_fma_f32 v[10:11], v[84:85], v[46:47], v[10:11] op_sel_hi:[0,1,1]
	v_fmac_f32_dpp v49, v38, v51 row_newbcast:12 row_mask:0xf bank_mask:0xf bound_ctrl:1
	v_pk_fma_f32 v[12:13], v[86:87], v[46:47], v[12:13] op_sel_hi:[0,1,1]
	v_pk_fma_f32 v[14:15], v[88:89], v[46:47], v[14:15] op_sel_hi:[0,1,1]
	v_cvt_pk_bf16_f32 v54, v48, v49
	v_pk_fma_f32 v[16:17], v[90:91], v[46:47], v[16:17] op_sel_hi:[0,1,1]
	v_pk_fma_f32 v[18:19], v[92:93], v[46:47], v[18:19] op_sel_hi:[0,1,1]
	v_pk_fma_f32 v[20:21], v[94:95], v[46:47], v[20:21] op_sel_hi:[0,1,1]
	global_store_dword v154, v54, s[14:15] offset:-4096
	s_waitcnt lgkmcnt(5)
	v_pk_mul_f32 v[38:39], v[6:7], v[56:57] op_sel_hi:[1,0]
	v_pk_mul_f32 v[40:41], v[6:7], v[56:57] op_sel:[0,1] op_sel_hi:[1,1]
	v_pk_fma_f32 v[38:39], v[8:9], v[58:59], v[38:39] op_sel_hi:[1,0,1]
	v_pk_fma_f32 v[40:41], v[8:9], v[58:59], v[40:41] op_sel:[0,1,0] op_sel_hi:[1,1,1]
	s_waitcnt lgkmcnt(4)
	v_pk_fma_f32 v[38:39], v[10:11], v[60:61], v[38:39] op_sel_hi:[1,0,1]
	v_pk_fma_f32 v[40:41], v[10:11], v[60:61], v[40:41] op_sel:[0,1,0] op_sel_hi:[1,1,1]
	v_pk_fma_f32 v[38:39], v[12:13], v[62:63], v[38:39] op_sel_hi:[1,0,1]
	v_pk_fma_f32 v[40:41], v[12:13], v[62:63], v[40:41] op_sel:[0,1,0] op_sel_hi:[1,1,1]
	s_waitcnt lgkmcnt(3)
	v_pk_fma_f32 v[38:39], v[14:15], v[64:65], v[38:39] op_sel_hi:[1,0,1]
	v_pk_fma_f32 v[40:41], v[14:15], v[64:65], v[40:41] op_sel:[0,1,0] op_sel_hi:[1,1,1]
	v_pk_fma_f32 v[38:39], v[16:17], v[66:67], v[38:39] op_sel_hi:[1,0,1]
	v_pk_fma_f32 v[40:41], v[16:17], v[66:67], v[40:41] op_sel:[0,1,0] op_sel_hi:[1,1,1]
	s_waitcnt lgkmcnt(2)
	v_pk_fma_f32 v[38:39], v[18:19], v[68:69], v[38:39] op_sel_hi:[1,0,1]
	v_pk_fma_f32 v[40:41], v[18:19], v[68:69], v[40:41] op_sel:[0,1,0] op_sel_hi:[1,1,1]
	v_pk_fma_f32 v[38:39], v[20:21], v[70:71], v[38:39] op_sel_hi:[1,0,1]
	v_pk_fma_f32 v[40:41], v[20:21], v[70:71], v[40:41] op_sel:[0,1,0] op_sel_hi:[1,1,1]
	s_waitcnt lgkmcnt(0)
	v_mul_f32_e32 v50, v76, v51
	v_add_f32_dpp v38, v38, v38 row_ror:8 row_mask:0xf bank_mask:0x3 bound_ctrl:1
	v_add_f32_dpp v39, v39, v39 row_ror:8 row_mask:0xf bank_mask:0x3 bound_ctrl:1
	v_add_f32_dpp v38, v40, v40 row_ror:8 row_mask:0xf bank_mask:0xc bound_ctrl:1
	v_add_f32_dpp v39, v41, v41 row_ror:8 row_mask:0xf bank_mask:0xc bound_ctrl:1
	ds_read_b128 v[80:83], v2 offset:36096
	v_add_f32_dpp v38, v38, v38 row_half_mirror row_mask:0xf bank_mask:0x5 bound_ctrl:1
	v_add_f32_dpp v38, v39, v39 row_half_mirror row_mask:0xf bank_mask:0xa bound_ctrl:1
	ds_read_b128 v[84:87], v2 offset:36352
	ds_read_b128 v[88:91], v2 offset:36608
	v_add_f32_dpp v38, v38, v38 quad_perm:[1,0,3,2] row_mask:0xf bank_mask:0xf bound_ctrl:1
	ds_read_b128 v[92:95], v2 offset:36864
	ds_read_b64 v[96:97], v3 offset:46080
	v_add_f32_dpp v38, v38, v38 quad_perm:[2,3,0,1] row_mask:0xf bank_mask:0xf bound_ctrl:1
	ds_read_b128 v[100:103], v1 offset:47408
	v_cmp_gt_f32_e32 vcc, 0x2b8cbccc, v50
	v_fmac_f32_dpp v72, -v38, v50 row_newbcast:0 row_mask:0xf bank_mask:0xf bound_ctrl:1
	v_fmac_f32_dpp v73, -v38, v50 row_newbcast:4 row_mask:0xf bank_mask:0xf bound_ctrl:1
	v_rcp_f32_e32 v52, v50
	s_add_u32 s14, s14, 0x1000
	v_pk_mul_f32 v[44:45], v[72:73], v[76:77] op_sel:[0,1] op_sel_hi:[1,1]
	s_addc_u32 s15, s15, 0
	s_cbranch_vccnz .Lgd2_rare2_2
.Lgd2_back2_2:
	v_pk_mul_f32 v[46:47], v[44:45], v[52:53] op_sel_hi:[1,0]
	v_pk_mul_f32 v[48:49], v[44:45], v[78:79] op_sel_hi:[1,0]
	v_pk_fma_f32 v[6:7], v[56:57], v[46:47], v[6:7] op_sel_hi:[0,1,1]
	v_pk_fma_f32 v[8:9], v[58:59], v[46:47], v[8:9] op_sel_hi:[0,1,1]
	v_fmac_f32_dpp v48, v38, v50 row_newbcast:8 row_mask:0xf bank_mask:0xf bound_ctrl:1
	v_pk_fma_f32 v[10:11], v[60:61], v[46:47], v[10:11] op_sel_hi:[0,1,1]
	v_fmac_f32_dpp v49, v38, v50 row_newbcast:12 row_mask:0xf bank_mask:0xf bound_ctrl:1
	v_pk_fma_f32 v[12:13], v[62:63], v[46:47], v[12:13] op_sel_hi:[0,1,1]
	v_pk_fma_f32 v[14:15], v[64:65], v[46:47], v[14:15] op_sel_hi:[0,1,1]
	v_cvt_pk_bf16_f32 v54, v48, v49
	v_pk_fma_f32 v[16:17], v[66:67], v[46:47], v[16:17] op_sel_hi:[0,1,1]
	v_pk_fma_f32 v[18:19], v[68:69], v[46:47], v[18:19] op_sel_hi:[0,1,1]
	v_pk_fma_f32 v[20:21], v[70:71], v[46:47], v[20:21] op_sel_hi:[0,1,1]
	global_store_dword v154, v54, s[14:15] offset:-4096
	s_waitcnt lgkmcnt(5)
	v_pk_mul_f32 v[38:39], v[6:7], v[80:81] op_sel_hi:[1,0]
	v_pk_mul_f32 v[40:41], v[6:7], v[80:81] op_sel:[0,1] op_sel_hi:[1,1]
	v_pk_fma_f32 v[38:39], v[8:9], v[82:83], v[38:39] op_sel_hi:[1,0,1]
	v_pk_fma_f32 v[40:41], v[8:9], v[82:83], v[40:41] op_sel:[0,1,0] op_sel_hi:[1,1,1]
	s_waitcnt lgkmcnt(4)
	v_pk_fma_f32 v[38:39], v[10:11], v[84:85], v[38:39] op_sel_hi:[1,0,1]
	v_pk_fma_f32 v[40:41], v[10:11], v[84:85], v[40:41] op_sel:[0,1,0] op_sel_hi:[1,1,1]
	v_pk_fma_f32 v[38:39], v[12:13], v[86:87], v[38:39] op_sel_hi:[1,0,1]
	v_pk_fma_f32 v[40:41], v[12:13], v[86:87], v[40:41] op_sel:[0,1,0] op_sel_hi:[1,1,1]
	s_waitcnt lgkmcnt(3)
	v_pk_fma_f32 v[38:39], v[14:15], v[88:89], v[38:39] op_sel_hi:[1,0,1]
	v_pk_fma_f32 v[40:41], v[14:15], v[88:89], v[40:41] op_sel:[0,1,0] op_sel_hi:[1,1,1]
	v_pk_fma_f32 v[38:39], v[16:17], v[90:91], v[38:39] op_sel_hi:[1,0,1]
	v_pk_fma_f32 v[40:41], v[16:17], v[90:91], v[40:41] op_sel:[0,1,0] op_sel_hi:[1,1,1]
	s_waitcnt lgkmcnt(2)
	v_pk_fma_f32 v[38:39], v[18:19], v[92:93], v[38:39] op_sel_hi:[1,0,1]
	v_pk_fma_f32 v[40:41], v[18:19], v[92:93], v[40:41] op_sel:[0,1,0] op_sel_hi:[1,1,1]
	v_pk_fma_f32 v[38:39], v[20:21], v[94:95], v[38:39] op_sel_hi:[1,0,1]
	v_pk_fma_f32 v[40:41], v[20:21], v[94:95], v[40:41] op_sel:[0,1,0] op_sel_hi:[1,1,1]
	s_waitcnt lgkmcnt(0)
	v_mul_f32_e32 v51, v100, v50
	v_add_f32_dpp v38, v38, v38 row_ror:8 row_mask:0xf bank_mask:0x3 bound_ctrl:1
	v_add_f32_dpp v39, v39, v39 row_ror:8 row_mask:0xf bank_mask:0x3 bound_ctrl:1
	v_add_f32_dpp v38, v40, v40 row_ror:8 row_mask:0xf bank_mask:0xc bound_ctrl:1
	v_add_f32_dpp v39, v41, v41 row_ror:8 row_mask:0xf bank_mask:0xc bound_ctrl:1
	ds_read_b128 v[56:59], v2 offset:37120
	v_add_f32_dpp v38, v38, v38 row_half_mirror row_mask:0xf bank_mask:0x5 bound_ctrl:1
	v_add_f32_dpp v38, v39, v39 row_half_mirror row_mask:0xf bank_mask:0xa bound_ctrl:1
	ds_read_b128 v[60:63], v2 offset:37376
	ds_read_b128 v[64:67], v2 offset:37632
	v_add_f32_dpp v38, v38, v38 quad_perm:[1,0,3,2] row_mask:0xf bank_mask:0xf bound_ctrl:1
	ds_read_b128 v[68:71], v2 offset:37888
	ds_read_b64 v[72:73], v3 offset:46336
	v_add_f32_dpp v38, v38, v38 quad_perm:[2,3,0,1] row_mask:0xf bank_mask:0xf bound_ctrl:1
	ds_read_b128 v[76:79], v1 offset:47424
	v_cmp_gt_f32_e32 vcc, 0x2b8cbccc, v51
	v_fmac_f32_dpp v96, -v38, v51 row_newbcast:0 row_mask:0xf bank_mask:0xf bound_ctrl:1
	v_fmac_f32_dpp v97, -v38, v51 row_newbcast:4 row_mask:0xf bank_mask:0xf bound_ctrl:1
	v_rcp_f32_e32 v52, v51
	s_add_u32 s14, s14, 0x1000
	v_pk_mul_f32 v[44:45], v[96:97], v[100:101] op_sel:[0,1] op_sel_hi:[1,1]
	s_addc_u32 s15, s15, 0
	s_cbranch_vccnz .Lgd2_rare2_3
.Lgd2_back2_3:
	v_pk_mul_f32 v[46:47], v[44:45], v[52:53] op_sel_hi:[1,0]
	v_pk_mul_f32 v[48:49], v[44:45], v[102:103] op_sel_hi:[1,0]
	v_pk_fma_f32 v[6:7], v[80:81], v[46:47], v[6:7] op_sel_hi:[0,1,1]
	v_pk_fma_f32 v[8:9], v[82:83], v[46:47], v[8:9] op_sel_hi:[0,1,1]
	v_fmac_f32_dpp v48, v38, v51 row_newbcast:8 row_mask:0xf bank_mask:0xf bound_ctrl:1
	v_pk_fma_f32 v[10:11], v[84:85], v[46:47], v[10:11] op_sel_hi:[0,1,1]
	v_fmac_f32_dpp v49, v38, v51 row_newbcast:12 row_mask:0xf bank_mask:0xf bound_ctrl:1
	v_pk_fma_f32 v[12:13], v[86:87], v[46:47], v[12:13] op_sel_hi:[0,1,1]
	v_pk_fma_f32 v[14:15], v[88:89], v[46:47], v[14:15] op_sel_hi:[0,1,1]
	v_cvt_pk_bf16_f32 v54, v48, v49
	v_pk_fma_f32 v[16:17], v[90:91], v[46:47], v[16:17] op_sel_hi:[0,1,1]
	v_pk_fma_f32 v[18:19], v[92:93], v[46:47], v[18:19] op_sel_hi:[0,1,1]
	v_pk_fma_f32 v[20:21], v[94:95], v[46:47], v[20:21] op_sel_hi:[0,1,1]
	global_store_dword v154, v54, s[14:15] offset:-4096
	s_waitcnt lgkmcnt(5)
	v_pk_mul_f32 v[38:39], v[6:7], v[56:57] op_sel_hi:[1,0]
	v_pk_mul_f32 v[40:41], v[6:7], v[56:57] op_sel:[0,1] op_sel_hi:[1,1]
	v_pk_fma_f32 v[38:39], v[8:9], v[58:59], v[38:39] op_sel_hi:[1,0,1]
	v_pk_fma_f32 v[40:41], v[8:9], v[58:59], v[40:41] op_sel:[0,1,0] op_sel_hi:[1,1,1]
	s_waitcnt lgkmcnt(4)
	v_pk_fma_f32 v[38:39], v[10:11], v[60:61], v[38:39] op_sel_hi:[1,0,1]
	v_pk_fma_f32 v[40:41], v[10:11], v[60:61], v[40:41] op_sel:[0,1,0] op_sel_hi:[1,1,1]
	v_pk_fma_f32 v[38:39], v[12:13], v[62:63], v[38:39] op_sel_hi:[1,0,1]
	v_pk_fma_f32 v[40:41], v[12:13], v[62:63], v[40:41] op_sel:[0,1,0] op_sel_hi:[1,1,1]
	s_waitcnt lgkmcnt(3)
	v_pk_fma_f32 v[38:39], v[14:15], v[64:65], v[38:39] op_sel_hi:[1,0,1]
	v_pk_fma_f32 v[40:41], v[14:15], v[64:65], v[40:41] op_sel:[0,1,0] op_sel_hi:[1,1,1]
	v_pk_fma_f32 v[38:39], v[16:17], v[66:67], v[38:39] op_sel_hi:[1,0,1]
	v_pk_fma_f32 v[40:41], v[16:17], v[66:67], v[40:41] op_sel:[0,1,0] op_sel_hi:[1,1,1]
	s_waitcnt lgkmcnt(2)
	v_pk_fma_f32 v[38:39], v[18:19], v[68:69], v[38:39] op_sel_hi:[1,0,1]
	v_pk_fma_f32 v[40:41], v[18:19], v[68:69], v[40:41] op_sel:[0,1,0] op_sel_hi:[1,1,1]
	v_pk_fma_f32 v[38:39], v[20:21], v[70:71], v[38:39] op_sel_hi:[1,0,1]
	v_pk_fma_f32 v[40:41], v[20:21], v[70:71], v[40:41] op_sel:[0,1,0] op_sel_hi:[1,1,1]
	s_waitcnt lgkmcnt(0)
	v_mul_f32_e32 v50, v76, v51
	v_add_f32_dpp v38, v38, v38 row_ror:8 row_mask:0xf bank_mask:0x3 bound_ctrl:1
	v_add_f32_dpp v39, v39, v39 row_ror:8 row_mask:0xf bank_mask:0x3 bound_ctrl:1
	v_add_f32_dpp v38, v40, v40 row_ror:8 row_mask:0xf bank_mask:0xc bound_ctrl:1
	v_add_f32_dpp v39, v41, v41 row_ror:8 row_mask:0xf bank_mask:0xc bound_ctrl:1
	ds_read_b128 v[80:83], v2 offset:38144
	v_add_f32_dpp v38, v38, v38 row_half_mirror row_mask:0xf bank_mask:0x5 bound_ctrl:1
	v_add_f32_dpp v38, v39, v39 row_half_mirror row_mask:0xf bank_mask:0xa bound_ctrl:1
	ds_read_b128 v[84:87], v2 offset:38400
	ds_read_b128 v[88:91], v2 offset:38656
	v_add_f32_dpp v38, v38, v38 quad_perm:[1,0,3,2] row_mask:0xf bank_mask:0xf bound_ctrl:1
	ds_read_b128 v[92:95], v2 offset:38912
	ds_read_b64 v[96:97], v3 offset:46592
	v_add_f32_dpp v38, v38, v38 quad_perm:[2,3,0,1] row_mask:0xf bank_mask:0xf bound_ctrl:1
	ds_read_b128 v[100:103], v1 offset:47440
	v_cmp_gt_f32_e32 vcc, 0x2b8cbccc, v50
	v_fmac_f32_dpp v72, -v38, v50 row_newbcast:0 row_mask:0xf bank_mask:0xf bound_ctrl:1
	v_fmac_f32_dpp v73, -v38, v50 row_newbcast:4 row_mask:0xf bank_mask:0xf bound_ctrl:1
	v_rcp_f32_e32 v52, v50
	s_add_u32 s14, s14, 0x1000
	v_pk_mul_f32 v[44:45], v[72:73], v[76:77] op_sel:[0,1] op_sel_hi:[1,1]
	s_addc_u32 s15, s15, 0
	s_cbranch_vccnz .Lgd2_rare2_4
.Lgd2_back2_4:
	v_pk_mul_f32 v[46:47], v[44:45], v[52:53] op_sel_hi:[1,0]
	v_pk_mul_f32 v[48:49], v[44:45], v[78:79] op_sel_hi:[1,0]
	v_pk_fma_f32 v[6:7], v[56:57], v[46:47], v[6:7] op_sel_hi:[0,1,1]
	v_pk_fma_f32 v[8:9], v[58:59], v[46:47], v[8:9] op_sel_hi:[0,1,1]
	v_fmac_f32_dpp v48, v38, v50 row_newbcast:8 row_mask:0xf bank_mask:0xf bound_ctrl:1
	v_pk_fma_f32 v[10:11], v[60:61], v[46:47], v[10:11] op_sel_hi:[0,1,1]
	v_fmac_f32_dpp v49, v38, v50 row_newbcast:12 row_mask:0xf bank_mask:0xf bound_ctrl:1
	v_pk_fma_f32 v[12:13], v[62:63], v[46:47], v[12:13] op_sel_hi:[0,1,1]
	v_pk_fma_f32 v[14:15], v[64:65], v[46:47], v[14:15] op_sel_hi:[0,1,1]
	v_cvt_pk_bf16_f32 v54, v48, v49
	v_pk_fma_f32 v[16:17], v[66:67], v[46:47], v[16:17] op_sel_hi:[0,1,1]
	v_pk_fma_f32 v[18:19], v[68:69], v[46:47], v[18:19] op_sel_hi:[0,1,1]
	v_pk_fma_f32 v[20:21], v[70:71], v[46:47], v[20:21] op_sel_hi:[0,1,1]
	global_store_dword v154, v54, s[14:15] offset:-4096
	s_waitcnt lgkmcnt(5)
	v_pk_mul_f32 v[38:39], v[6:7], v[80:81] op_sel_hi:[1,0]
	v_pk_mul_f32 v[40:41], v[6:7], v[80:81] op_sel:[0,1] op_sel_hi:[1,1]
	v_pk_fma_f32 v[38:39], v[8:9], v[82:83], v[38:39] op_sel_hi:[1,0,1]
	v_pk_fma_f32 v[40:41], v[8:9], v[82:83], v[40:41] op_sel:[0,1,0] op_sel_hi:[1,1,1]
	s_waitcnt lgkmcnt(4)
	v_pk_fma_f32 v[38:39], v[10:11], v[84:85], v[38:39] op_sel_hi:[1,0,1]
	v_pk_fma_f32 v[40:41], v[10:11], v[84:85], v[40:41] op_sel:[0,1,0] op_sel_hi:[1,1,1]
	v_pk_fma_f32 v[38:39], v[12:13], v[86:87], v[38:39] op_sel_hi:[1,0,1]
	v_pk_fma_f32 v[40:41], v[12:13], v[86:87], v[40:41] op_sel:[0,1,0] op_sel_hi:[1,1,1]
	s_waitcnt lgkmcnt(3)
	v_pk_fma_f32 v[38:39], v[14:15], v[88:89], v[38:39] op_sel_hi:[1,0,1]
	v_pk_fma_f32 v[40:41], v[14:15], v[88:89], v[40:41] op_sel:[0,1,0] op_sel_hi:[1,1,1]
	v_pk_fma_f32 v[38:39], v[16:17], v[90:91], v[38:39] op_sel_hi:[1,0,1]
	v_pk_fma_f32 v[40:41], v[16:17], v[90:91], v[40:41] op_sel:[0,1,0] op_sel_hi:[1,1,1]
	s_waitcnt lgkmcnt(2)
	v_pk_fma_f32 v[38:39], v[18:19], v[92:93], v[38:39] op_sel_hi:[1,0,1]
	v_pk_fma_f32 v[40:41], v[18:19], v[92:93], v[40:41] op_sel:[0,1,0] op_sel_hi:[1,1,1]
	v_pk_fma_f32 v[38:39], v[20:21], v[94:95], v[38:39] op_sel_hi:[1,0,1]
	v_pk_fma_f32 v[40:41], v[20:21], v[94:95], v[40:41] op_sel:[0,1,0] op_sel_hi:[1,1,1]
	s_waitcnt lgkmcnt(0)
	v_mul_f32_e32 v51, v100, v50
	v_add_f32_dpp v38, v38, v38 row_ror:8 row_mask:0xf bank_mask:0x3 bound_ctrl:1
	v_add_f32_dpp v39, v39, v39 row_ror:8 row_mask:0xf bank_mask:0x3 bound_ctrl:1
	v_add_f32_dpp v38, v40, v40 row_ror:8 row_mask:0xf bank_mask:0xc bound_ctrl:1
	v_add_f32_dpp v39, v41, v41 row_ror:8 row_mask:0xf bank_mask:0xc bound_ctrl:1
	ds_read_b128 v[56:59], v2 offset:39168
	v_add_f32_dpp v38, v38, v38 row_half_mirror row_mask:0xf bank_mask:0x5 bound_ctrl:1
	v_add_f32_dpp v38, v39, v39 row_half_mirror row_mask:0xf bank_mask:0xa bound_ctrl:1
	ds_read_b128 v[60:63], v2 offset:39424
	ds_read_b128 v[64:67], v2 offset:39680
	v_add_f32_dpp v38, v38, v38 quad_perm:[1,0,3,2] row_mask:0xf bank_mask:0xf bound_ctrl:1
	ds_read_b128 v[68:71], v2 offset:39936
	ds_read_b64 v[72:73], v3 offset:46848
	v_add_f32_dpp v38, v38, v38 quad_perm:[2,3,0,1] row_mask:0xf bank_mask:0xf bound_ctrl:1
	ds_read_b128 v[76:79], v1 offset:47456
	v_cmp_gt_f32_e32 vcc, 0x2b8cbccc, v51
	v_fmac_f32_dpp v96, -v38, v51 row_newbcast:0 row_mask:0xf bank_mask:0xf bound_ctrl:1
	v_fmac_f32_dpp v97, -v38, v51 row_newbcast:4 row_mask:0xf bank_mask:0xf bound_ctrl:1
	v_rcp_f32_e32 v52, v51
	s_add_u32 s14, s14, 0x1000
	v_pk_mul_f32 v[44:45], v[96:97], v[100:101] op_sel:[0,1] op_sel_hi:[1,1]
	s_addc_u32 s15, s15, 0
	s_cbranch_vccnz .Lgd2_rare2_5
.Lgd2_back2_5:
	v_pk_mul_f32 v[46:47], v[44:45], v[52:53] op_sel_hi:[1,0]
	v_pk_mul_f32 v[48:49], v[44:45], v[102:103] op_sel_hi:[1,0]
	v_pk_fma_f32 v[6:7], v[80:81], v[46:47], v[6:7] op_sel_hi:[0,1,1]
	v_pk_fma_f32 v[8:9], v[82:83], v[46:47], v[8:9] op_sel_hi:[0,1,1]
	v_fmac_f32_dpp v48, v38, v51 row_newbcast:8 row_mask:0xf bank_mask:0xf bound_ctrl:1
	v_pk_fma_f32 v[10:11], v[84:85], v[46:47], v[10:11] op_sel_hi:[0,1,1]
	v_fmac_f32_dpp v49, v38, v51 row_newbcast:12 row_mask:0xf bank_mask:0xf bound_ctrl:1
	v_pk_fma_f32 v[12:13], v[86:87], v[46:47], v[12:13] op_sel_hi:[0,1,1]
	v_pk_fma_f32 v[14:15], v[88:89], v[46:47], v[14:15] op_sel_hi:[0,1,1]
	v_cvt_pk_bf16_f32 v54, v48, v49
	v_pk_fma_f32 v[16:17], v[90:91], v[46:47], v[16:17] op_sel_hi:[0,1,1]
	v_pk_fma_f32 v[18:19], v[92:93], v[46:47], v[18:19] op_sel_hi:[0,1,1]
	v_pk_fma_f32 v[20:21], v[94:95], v[46:47], v[20:21] op_sel_hi:[0,1,1]
	global_store_dword v154, v54, s[14:15] offset:-4096
	s_waitcnt lgkmcnt(5)
	v_pk_mul_f32 v[38:39], v[6:7], v[56:57] op_sel_hi:[1,0]
	v_pk_mul_f32 v[40:41], v[6:7], v[56:57] op_sel:[0,1] op_sel_hi:[1,1]
	v_pk_fma_f32 v[38:39], v[8:9], v[58:59], v[38:39] op_sel_hi:[1,0,1]
	v_pk_fma_f32 v[40:41], v[8:9], v[58:59], v[40:41] op_sel:[0,1,0] op_sel_hi:[1,1,1]
	s_waitcnt lgkmcnt(4)
	v_pk_fma_f32 v[38:39], v[10:11], v[60:61], v[38:39] op_sel_hi:[1,0,1]
	v_pk_fma_f32 v[40:41], v[10:11], v[60:61], v[40:41] op_sel:[0,1,0] op_sel_hi:[1,1,1]
	v_pk_fma_f32 v[38:39], v[12:13], v[62:63], v[38:39] op_sel_hi:[1,0,1]
	v_pk_fma_f32 v[40:41], v[12:13], v[62:63], v[40:41] op_sel:[0,1,0] op_sel_hi:[1,1,1]
	s_waitcnt lgkmcnt(3)
	v_pk_fma_f32 v[38:39], v[14:15], v[64:65], v[38:39] op_sel_hi:[1,0,1]
	v_pk_fma_f32 v[40:41], v[14:15], v[64:65], v[40:41] op_sel:[0,1,0] op_sel_hi:[1,1,1]
	v_pk_fma_f32 v[38:39], v[16:17], v[66:67], v[38:39] op_sel_hi:[1,0,1]
	v_pk_fma_f32 v[40:41], v[16:17], v[66:67], v[40:41] op_sel:[0,1,0] op_sel_hi:[1,1,1]
	s_waitcnt lgkmcnt(2)
	v_pk_fma_f32 v[38:39], v[18:19], v[68:69], v[38:39] op_sel_hi:[1,0,1]
	v_pk_fma_f32 v[40:41], v[18:19], v[68:69], v[40:41] op_sel:[0,1,0] op_sel_hi:[1,1,1]
	v_pk_fma_f32 v[38:39], v[20:21], v[70:71], v[38:39] op_sel_hi:[1,0,1]
	v_pk_fma_f32 v[40:41], v[20:21], v[70:71], v[40:41] op_sel:[0,1,0] op_sel_hi:[1,1,1]
	s_waitcnt lgkmcnt(0)
	v_mul_f32_e32 v50, v76, v51
	v_add_f32_dpp v38, v38, v38 row_ror:8 row_mask:0xf bank_mask:0x3 bound_ctrl:1
	v_add_f32_dpp v39, v39, v39 row_ror:8 row_mask:0xf bank_mask:0x3 bound_ctrl:1
	v_add_f32_dpp v38, v40, v40 row_ror:8 row_mask:0xf bank_mask:0xc bound_ctrl:1
	v_add_f32_dpp v39, v41, v41 row_ror:8 row_mask:0xf bank_mask:0xc bound_ctrl:1
	ds_read_b128 v[80:83], v2 offset:40192
	v_add_f32_dpp v38, v38, v38 row_half_mirror row_mask:0xf bank_mask:0x5 bound_ctrl:1
	v_add_f32_dpp v38, v39, v39 row_half_mirror row_mask:0xf bank_mask:0xa bound_ctrl:1
	ds_read_b128 v[84:87], v2 offset:40448
	ds_read_b128 v[88:91], v2 offset:40704
	v_add_f32_dpp v38, v38, v38 quad_perm:[1,0,3,2] row_mask:0xf bank_mask:0xf bound_ctrl:1
	ds_read_b128 v[92:95], v2 offset:40960
	ds_read_b64 v[96:97], v3 offset:47104
	v_add_f32_dpp v38, v38, v38 quad_perm:[2,3,0,1] row_mask:0xf bank_mask:0xf bound_ctrl:1
	ds_read_b128 v[100:103], v1 offset:47472
	v_cmp_gt_f32_e32 vcc, 0x2b8cbccc, v50
	v_fmac_f32_dpp v72, -v38, v50 row_newbcast:0 row_mask:0xf bank_mask:0xf bound_ctrl:1
	v_fmac_f32_dpp v73, -v38, v50 row_newbcast:4 row_mask:0xf bank_mask:0xf bound_ctrl:1
	v_rcp_f32_e32 v52, v50
	s_add_u32 s14, s14, 0x1000
	v_pk_mul_f32 v[44:45], v[72:73], v[76:77] op_sel:[0,1] op_sel_hi:[1,1]
	s_addc_u32 s15, s15, 0
	s_cbranch_vccnz .Lgd2_rare2_6
.Lgd2_back2_6:
	v_pk_mul_f32 v[46:47], v[44:45], v[52:53] op_sel_hi:[1,0]
	v_pk_mul_f32 v[48:49], v[44:45], v[78:79] op_sel_hi:[1,0]
	v_pk_fma_f32 v[6:7], v[56:57], v[46:47], v[6:7] op_sel_hi:[0,1,1]
	v_pk_fma_f32 v[8:9], v[58:59], v[46:47], v[8:9] op_sel_hi:[0,1,1]
	v_fmac_f32_dpp v48, v38, v50 row_newbcast:8 row_mask:0xf bank_mask:0xf bound_ctrl:1
	v_pk_fma_f32 v[10:11], v[60:61], v[46:47], v[10:11] op_sel_hi:[0,1,1]
	v_fmac_f32_dpp v49, v38, v50 row_newbcast:12 row_mask:0xf bank_mask:0xf bound_ctrl:1
	v_pk_fma_f32 v[12:13], v[62:63], v[46:47], v[12:13] op_sel_hi:[0,1,1]
	v_pk_fma_f32 v[14:15], v[64:65], v[46:47], v[14:15] op_sel_hi:[0,1,1]
	v_cvt_pk_bf16_f32 v54, v48, v49
	v_pk_fma_f32 v[16:17], v[66:67], v[46:47], v[16:17] op_sel_hi:[0,1,1]
	v_pk_fma_f32 v[18:19], v[68:69], v[46:47], v[18:19] op_sel_hi:[0,1,1]
	v_pk_fma_f32 v[20:21], v[70:71], v[46:47], v[20:21] op_sel_hi:[0,1,1]
	global_store_dword v154, v54, s[14:15] offset:-4096
	s_waitcnt lgkmcnt(5)
	v_pk_mul_f32 v[38:39], v[6:7], v[80:81] op_sel_hi:[1,0]
	v_pk_mul_f32 v[40:41], v[6:7], v[80:81] op_sel:[0,1] op_sel_hi:[1,1]
	v_pk_fma_f32 v[38:39], v[8:9], v[82:83], v[38:39] op_sel_hi:[1,0,1]
	v_pk_fma_f32 v[40:41], v[8:9], v[82:83], v[40:41] op_sel:[0,1,0] op_sel_hi:[1,1,1]
	s_waitcnt lgkmcnt(4)
	v_pk_fma_f32 v[38:39], v[10:11], v[84:85], v[38:39] op_sel_hi:[1,0,1]
	v_pk_fma_f32 v[40:41], v[10:11], v[84:85], v[40:41] op_sel:[0,1,0] op_sel_hi:[1,1,1]
	v_pk_fma_f32 v[38:39], v[12:13], v[86:87], v[38:39] op_sel_hi:[1,0,1]
	v_pk_fma_f32 v[40:41], v[12:13], v[86:87], v[40:41] op_sel:[0,1,0] op_sel_hi:[1,1,1]
	s_waitcnt lgkmcnt(3)
	v_pk_fma_f32 v[38:39], v[14:15], v[88:89], v[38:39] op_sel_hi:[1,0,1]
	v_pk_fma_f32 v[40:41], v[14:15], v[88:89], v[40:41] op_sel:[0,1,0] op_sel_hi:[1,1,1]
	v_pk_fma_f32 v[38:39], v[16:17], v[90:91], v[38:39] op_sel_hi:[1,0,1]
	v_pk_fma_f32 v[40:41], v[16:17], v[90:91], v[40:41] op_sel:[0,1,0] op_sel_hi:[1,1,1]
	s_waitcnt lgkmcnt(2)
	v_pk_fma_f32 v[38:39], v[18:19], v[92:93], v[38:39] op_sel_hi:[1,0,1]
	v_pk_fma_f32 v[40:41], v[18:19], v[92:93], v[40:41] op_sel:[0,1,0] op_sel_hi:[1,1,1]
	v_pk_fma_f32 v[38:39], v[20:21], v[94:95], v[38:39] op_sel_hi:[1,0,1]
	v_pk_fma_f32 v[40:41], v[20:21], v[94:95], v[40:41] op_sel:[0,1,0] op_sel_hi:[1,1,1]
	s_waitcnt lgkmcnt(0)
	v_mul_f32_e32 v51, v100, v50
	v_add_f32_dpp v38, v38, v38 row_ror:8 row_mask:0xf bank_mask:0x3 bound_ctrl:1
	v_add_f32_dpp v39, v39, v39 row_ror:8 row_mask:0xf bank_mask:0x3 bound_ctrl:1
	v_add_f32_dpp v38, v40, v40 row_ror:8 row_mask:0xf bank_mask:0xc bound_ctrl:1
	v_add_f32_dpp v39, v41, v41 row_ror:8 row_mask:0xf bank_mask:0xc bound_ctrl:1
	ds_read_b128 v[56:59], v2 offset:256
	v_add_f32_dpp v38, v38, v38 row_half_mirror row_mask:0xf bank_mask:0x5 bound_ctrl:1
	v_add_f32_dpp v38, v39, v39 row_half_mirror row_mask:0xf bank_mask:0xa bound_ctrl:1
	ds_read_b128 v[60:63], v2 offset:512
	ds_read_b128 v[64:67], v2 offset:768
	v_add_f32_dpp v38, v38, v38 quad_perm:[1,0,3,2] row_mask:0xf bank_mask:0xf bound_ctrl:1
	ds_read_b128 v[68:71], v2 offset:1024
	ds_read_b64 v[72:73], v3 offset:12544
	v_add_f32_dpp v38, v38, v38 quad_perm:[2,3,0,1] row_mask:0xf bank_mask:0xf bound_ctrl:1
	ds_read_b128 v[76:79], v1 offset:14592
	v_cmp_gt_f32_e32 vcc, 0x2b8cbccc, v51
	v_fmac_f32_dpp v96, -v38, v51 row_newbcast:0 row_mask:0xf bank_mask:0xf bound_ctrl:1
	v_fmac_f32_dpp v97, -v38, v51 row_newbcast:4 row_mask:0xf bank_mask:0xf bound_ctrl:1
	v_rcp_f32_e32 v52, v51
	s_add_u32 s14, s14, 0x1000
	v_pk_mul_f32 v[44:45], v[96:97], v[100:101] op_sel:[0,1] op_sel_hi:[1,1]
	s_addc_u32 s15, s15, 0
	s_cbranch_vccnz .Lgd2_rare2_7
.Lgd2_back2_7:
	v_pk_mul_f32 v[46:47], v[44:45], v[52:53] op_sel_hi:[1,0]
	v_pk_mul_f32 v[48:49], v[44:45], v[102:103] op_sel_hi:[1,0]
	v_pk_fma_f32 v[6:7], v[80:81], v[46:47], v[6:7] op_sel_hi:[0,1,1]
	v_pk_fma_f32 v[8:9], v[82:83], v[46:47], v[8:9] op_sel_hi:[0,1,1]
	v_fmac_f32_dpp v48, v38, v51 row_newbcast:8 row_mask:0xf bank_mask:0xf bound_ctrl:1
	v_pk_fma_f32 v[10:11], v[84:85], v[46:47], v[10:11] op_sel_hi:[0,1,1]
	v_fmac_f32_dpp v49, v38, v51 row_newbcast:12 row_mask:0xf bank_mask:0xf bound_ctrl:1
	v_pk_fma_f32 v[12:13], v[86:87], v[46:47], v[12:13] op_sel_hi:[0,1,1]
	v_pk_fma_f32 v[14:15], v[88:89], v[46:47], v[14:15] op_sel_hi:[0,1,1]
	v_cvt_pk_bf16_f32 v54, v48, v49
	v_pk_fma_f32 v[16:17], v[90:91], v[46:47], v[16:17] op_sel_hi:[0,1,1]
	v_pk_fma_f32 v[18:19], v[92:93], v[46:47], v[18:19] op_sel_hi:[0,1,1]
	v_pk_fma_f32 v[20:21], v[94:95], v[46:47], v[20:21] op_sel_hi:[0,1,1]
	global_store_dword v154, v54, s[14:15] offset:-4096
	s_waitcnt vmcnt(8)
	v_lshlrev_b32_e32 v116, 16, v108
	v_lshlrev_b32_e32 v117, 16, v109
	v_and_b32_e32 v118, s17, v108
	v_and_b32_e32 v119, s17, v109
	v_lshlrev_b32_e32 v120, 16, v110
	v_and_b32_e32 v121, s17, v110
	v_lshlrev_b32_e32 v122, 16, v111
	v_and_b32_e32 v123, s17, v111
	v_lshlrev_b32_e32 v124, 16, v112
	v_and_b32_e32 v125, s17, v112
	ds_write_b128 v32, v[116:119] offset:16640
	ds_write_b64 v33, v[120:121] offset:16640
	ds_write_b64 v34, v[122:123] offset:16640
	ds_write_b64 v34, v[124:125] offset:16768
	ds_write_b32 v35, v113 offset:16640
	s_add_i32 s16, s16, 8
	s_waitcnt lgkmcnt(0)
	s_barrier
	s_cmpk_lt_u32 s16, 0x800
	s_cbranch_scc1 .Lgd2_loop

.Lgd2_rare0_0:
	v_pk_mul_f32 v[6:7], v[6:7], v[50:51] op_sel:[0,0] op_sel_hi:[1,0]
	v_pk_mul_f32 v[8:9], v[8:9], v[50:51] op_sel:[0,0] op_sel_hi:[1,0]
	v_pk_mul_f32 v[10:11], v[10:11], v[50:51] op_sel:[0,0] op_sel_hi:[1,0]
	v_pk_mul_f32 v[12:13], v[12:13], v[50:51] op_sel:[0,0] op_sel_hi:[1,0]
	v_pk_mul_f32 v[14:15], v[14:15], v[50:51] op_sel:[0,0] op_sel_hi:[1,0]
	v_pk_mul_f32 v[16:17], v[16:17], v[50:51] op_sel:[0,0] op_sel_hi:[1,0]
	v_pk_mul_f32 v[18:19], v[18:19], v[50:51] op_sel:[0,0] op_sel_hi:[1,0]
	v_pk_mul_f32 v[20:21], v[20:21], v[50:51] op_sel:[0,0] op_sel_hi:[1,0]
	v_mul_f32_e32 v38, v38, v50
	v_mov_b32_e32 v50, 1.0
	v_mov_b32_e32 v52, 1.0
	s_branch .Lgd2_back0_0
.Lgd2_rare0_1:
	v_pk_mul_f32 v[6:7], v[6:7], v[50:51] op_sel:[0,1] op_sel_hi:[1,1]
	v_pk_mul_f32 v[8:9], v[8:9], v[50:51] op_sel:[0,1] op_sel_hi:[1,1]
	v_pk_mul_f32 v[10:11], v[10:11], v[50:51] op_sel:[0,1] op_sel_hi:[1,1]
	v_pk_mul_f32 v[12:13], v[12:13], v[50:51] op_sel:[0,1] op_sel_hi:[1,1]
	v_pk_mul_f32 v[14:15], v[14:15], v[50:51] op_sel:[0,1] op_sel_hi:[1,1]
	v_pk_mul_f32 v[16:17], v[16:17], v[50:51] op_sel:[0,1] op_sel_hi:[1,1]
	v_pk_mul_f32 v[18:19], v[18:19], v[50:51] op_sel:[0,1] op_sel_hi:[1,1]
	v_pk_mul_f32 v[20:21], v[20:21], v[50:51] op_sel:[0,1] op_sel_hi:[1,1]
	v_mul_f32_e32 v38, v38, v51
	v_mov_b32_e32 v51, 1.0
	v_mov_b32_e32 v52, 1.0
	s_branch .Lgd2_back0_1
